# attention: per-segment s_setprio flips removed, one static s_setprio 1 for waves 4-7 during the attention unit loop (on top of v030)
# speedup vs baseline: 1.0040x; 1.0040x over previous
; #define DEAL_LOOP(F, ctr, N, BODY) do { gu32* _c = (ctr); int u = F.bid; while (u < (N)) { const unsigned _t = deal_prefetch(F, _c); BODY; u = deal_publish(F, _t) + F.G; } __syncthreads(); } while (0)
; #define REPBAR(k) do { if (rep + 1 < REPS(k)) xcd_barrier(bar); } while (0)
; #define LAUNDER() do { launder(F); GAS unsigned char* _g = (GAS unsigned char*)ws; asm volatile("" : "+s"(_g)); ws = (unsigned char*)_g; } while (0)
; __global__ void __launch_bounds__(NTHR, 2) fwd(Args args) {
;     ...
;             for (int rep = 0; rep < REPS(8); ++rep) { LAUNDER();
;                 if (PH_ON(8)) DEAL_LOOP(F, cnt_word(F, l, CNT_ATTN + 5 * rep), AT_UNITS, attn_unit<0>(args, F, l, u));
;                 REPBAR(8); }
.LBB0_1366:
	s_or_b64 exec, exec, s[2:3]
	s_lshl_b32 s4, s90, 10
	v_readlane_b32 s0, v249, 25
	s_add_u32 s0, s74, s0
	s_mov_b32 s5, s63
	v_writelane_b32 v249, s0, 31
	s_addc_u32 s0, s75, 0
	s_cmpk_lt_i32 s69, 0x240
	v_cmp_eq_u32_e64 s[36:37], 0, v0
	v_writelane_b32 v249, s0, 32
	s_cbranch_scc0 .LBB0_1420
	s_lshl_b64 s[0:1], s[4:5], 2
	s_add_u32 s0, s74, s0
	s_addc_u32 s1, s75, s1
	s_add_u32 s6, s0, 0x10c00
	s_addc_u32 s7, s1, 0
	s_and_b32 s101, s69, 7
	s_lshl_b32 s101, s101, 7
	s_add_u32 s6, s6, s101
	s_addc_u32 s7, s7, 0
	v_readlane_b32 s2, v249, 31
	s_add_u32 s8, s2, 0x3b86000
	v_readlane_b32 s3, v249, 32
	v_readlane_b32 s12, v250, 60
	s_addc_u32 s9, s3, 0
	s_lshl_b32 s62, s90, 6
	v_readlane_b32 s22, v251, 6
	v_readlane_b32 s23, v251, 7
	v_readlane_b32 s26, v251, 10
	v_readlane_b32 s27, v251, 11
	s_lshl_b32 s33, s90, 24
	s_lshl_b64 s[0:1], s[62:63], 2
	s_mov_b64 s[22:23], s[26:27]
	s_add_u32 s10, s22, s0
	s_addc_u32 s11, s23, s1
	v_readlane_b32 s13, v250, 61
	v_readlane_b32 s20, v251, 4
	s_add_u32 s12, s2, 0x3b86004
	s_addc_u32 s13, s3, 0
	s_mov_b32 s20, s69
	v_readlane_b32 s14, v250, 62
	v_readlane_b32 s15, v250, 63
	v_readlane_b32 s16, v251, 0
	v_readlane_b32 s17, v251, 1
	v_readlane_b32 s18, v251, 2
	v_readlane_b32 s19, v251, 3
	v_readlane_b32 s21, v251, 5
	v_readlane_b32 s24, v251, 8
	v_readlane_b32 s25, v251, 9
	s_cmp_lt_u32 s78, 4
	s_cbranch_scc1 .Lprio_skip
	s_setprio 1
.Lprio_skip:
	s_branch .LBB0_1369
.LBB0_1368:
	s_or_b64 exec, exec, s[0:1]
	v_mov_b32_e32 v3, s79
	s_waitcnt lgkmcnt(0)
	s_barrier
	ds_read_b32 v3, v3
	s_waitcnt lgkmcnt(0)
	v_readfirstlane_b32 s0, v3
	s_lshl_b32 s0, s0, 3
	s_add_i32 s20, s0, s76
	s_and_b32 s101, s69, 7
	s_add_i32 s20, s20, s101
	s_cmpk_lt_i32 s20, 0x240
	s_cbranch_scc0 .LBB0_1420

; #define LAS __attribute__((address_space(3)))
; DI float fast_exp2(float x) { return __builtin_amdgcn_exp2f(x); }
; #define MFMA16(a, b, c) __builtin_amdgcn_mfma_f32_16x16x32_bf16((a), (b), (c), 0, 0, 0)
; DI void at_qk(f32x4 (&s1)[4], f32x4 (&s2)[4], const LAS unsigned char* buf, const bf16x8 q1, const bf16x8 q2, const f32x4 (&ci)[4], int hh, int fr, int fq) {
; #pragma unroll
;     for (int k4 = 0; k4 < 4; ++k4) { const LAS unsigned char* kr = buf + AT_K + (16 * k4 + fr) * 272 + hh * 128 + fq * 16;
;         s1[k4] = MFMA16(ld8l(kr), q1, ci[k4]); s2[k4] = MFMA16(ld8l(kr + 64), q2, ci[k4]); }
; }
; DI void at_exp(f32x4 (&s1)[4], f32x4 (&s2)[4], float& ps1, float& ps2) {
;     f32x4 a1 = (f32x4){0.f, 0.f, 0.f, 0.f}, a2 = a1;
; #pragma unroll
;     for (int k4 = 0; k4 < 4; ++k4) {
; #pragma unroll
;         for (int j = 0; j < 4; ++j) { s1[k4][j] = fast_exp2(s1[k4][j]); s2[k4][j] = fast_exp2(s2[k4][j]); }
;         a1 = a1 + s1[k4]; a2 = a2 + s2[k4]; }
;     ps1 = (a1[0] + a1[1]) + (a1[2] + a1[3]); ps2 = (a2[0] + a2[1]) + (a2[2] + a2[3]);
; template <int VAR>
; DI void attn_tile(AtState& S, const LAS unsigned char* buf, const bf16x8 q1, const bf16x8 q2, int kt, bool diag, int qpos0, int qpos_l, float slope2, float adv, float decay, int hh, int fr, int fq) {
;     ...
;         asm volatile("; attention: fast tile" ::: "memory");
;         at_qk(s1, s2, buf, q1, q2, S.cinit, hh, fr, fq);
;         S.ref += adv;
;         at_exp(s1, s2, ps1, ps2);
;         if (__any(!(ps1 + ps2 < 0x1p60f))) {
;             asm volatile("; attention: bump" ::: "memory");
;             at_qk(s1, s2, buf, q1, q2, S.cinit, hh, fr, fq);
;             float lm = -1e30f;
; #pragma unroll
;             for (int k4 = 0; k4 < 4; ++k4)
; #pragma unroll
;                 for (int j = 0; j < 4; ++j) lm = fmaxf(lm, fmaxf(s1[k4][j], s2[k4][j]));
;             lm = fmaxf(lm, __shfl_xor(lm, 16)); lm = fmaxf(lm, __shfl_xor(lm, 32));
.LBB0_1376:
	s_add_i32 s27, s26, -1
	s_min_i32 s14, s27, s25
	s_ashr_i32 s15, s14, 31
	s_add_i32 s28, s22, s26
	s_lshl_b64 s[14:15], s[14:15], 18
	s_add_u32 s14, s0, s14
	s_addc_u32 s15, s1, s15
	global_load_dwordx4 v[28:31], v144, s[14:15] offset:1024
	global_load_dwordx4 v[32:35], v144, s[14:15] offset:1536
	global_load_dwordx4 v[36:39], v146, s[14:15] offset:1024
	global_load_dwordx4 v[40:43], v146, s[14:15] offset:1536
	s_cmpk_eq_i32 s28, 0x42
	s_cselect_b64 s[16:17], -1, 0
	s_cmp_eq_u32 s26, 3
	s_cselect_b64 s[14:15], -1, 0
	s_or_b64 s[18:19], s[14:15], s[16:17]
	s_andn2_b64 vcc, exec, s[18:19]
	s_mov_b64 s[18:19], -1
	s_cbranch_vccz .LBB0_1381
	ds_read_b128 v[76:79], v213
	ds_read_b128 v[80:83], v213 offset:64
	ds_read_b128 v[96:99], v213 offset:4352
	ds_read_b128 v[104:107], v213 offset:4416
	ds_read_b128 v[108:111], v213 offset:8704
	ds_read_b128 v[112:115], v213 offset:8768
	ds_read_b128 v[116:119], v213 offset:13056
	ds_read_b128 v[120:123], v213 offset:13120
	s_waitcnt lgkmcnt(7)
	v_mfma_f32_16x16x32_bf16 v[76:79], v[76:79], v[4:7], v[44:47]
	v_add_f32_e32 v215, v205, v214
	s_waitcnt lgkmcnt(6)
	v_mfma_f32_16x16x32_bf16 v[80:83], v[80:83], v[8:11], v[44:47]
	s_waitcnt lgkmcnt(5)
	v_mfma_f32_16x16x32_bf16 v[96:99], v[96:99], v[4:7], v[48:51]
	s_nop 2
	v_exp_f32_e32 v164, v76
	v_exp_f32_e32 v165, v77
	v_exp_f32_e32 v168, v78
	s_waitcnt lgkmcnt(4)
	v_mfma_f32_16x16x32_bf16 v[104:107], v[104:107], v[8:11], v[48:51]
	v_exp_f32_e32 v169, v79
	v_exp_f32_e32 v162, v80
	v_exp_f32_e32 v163, v81
	s_waitcnt lgkmcnt(3)
	v_mfma_f32_16x16x32_bf16 v[108:111], v[108:111], v[4:7], v[52:55]
	v_exp_f32_e32 v166, v82
	v_exp_f32_e32 v167, v83
	v_exp_f32_e32 v172, v96
	s_waitcnt lgkmcnt(2)
	v_mfma_f32_16x16x32_bf16 v[76:79], v[112:115], v[8:11], v[52:55]
	v_exp_f32_e32 v170, v104
	v_exp_f32_e32 v173, v97
	v_exp_f32_e32 v176, v98
	s_waitcnt lgkmcnt(1)
	v_mfma_f32_16x16x32_bf16 v[80:83], v[116:119], v[4:7], v[56:59]
	v_exp_f32_e32 v177, v99
	v_exp_f32_e32 v174, v106
	v_exp_f32_e32 v175, v107
	s_waitcnt lgkmcnt(0)
	v_mfma_f32_16x16x32_bf16 v[112:115], v[120:123], v[8:11], v[56:59]
	v_exp_f32_e32 v171, v105
	v_exp_f32_e32 v180, v108
	v_exp_f32_e32 v178, v76
	v_exp_f32_e32 v181, v109
	v_exp_f32_e32 v179, v77
	v_exp_f32_e32 v184, v110
	v_exp_f32_e32 v185, v111
	v_exp_f32_e32 v182, v78
	v_exp_f32_e32 v183, v79
	v_exp_f32_e32 v188, v80
	v_exp_f32_e32 v186, v112
	v_exp_f32_e32 v189, v81
	v_exp_f32_e32 v192, v82
	v_exp_f32_e32 v193, v83
	v_exp_f32_e32 v190, v114
	v_exp_f32_e32 v191, v115
	v_exp_f32_e32 v187, v113
	v_pk_add_f32 v[96:97], v[168:169], v[176:177]
	v_pk_add_f32 v[98:99], v[164:165], v[172:173]
	v_pk_add_f32 v[104:105], v[166:167], v[174:175]
	v_pk_add_f32 v[106:107], v[162:163], v[170:171]
	v_pk_add_f32 v[76:77], v[98:99], v[180:181]
	v_pk_add_f32 v[78:79], v[96:97], v[184:185]
	v_pk_add_f32 v[96:97], v[106:107], v[178:179]
	v_pk_add_f32 v[98:99], v[104:105], v[182:183]
	v_pk_add_f32 v[78:79], v[78:79], v[192:193]
	v_pk_add_f32 v[76:77], v[76:77], v[188:189]
	v_pk_add_f32 v[80:81], v[98:99], v[190:191]
	v_pk_add_f32 v[82:83], v[96:97], v[186:187]
	v_mov_b32_e32 v97, v76
	v_mov_b32_e32 v96, v82
	v_mov_b32_e32 v76, v83
	v_mov_b32_e32 v82, v80
	v_mov_b32_e32 v83, v78
	v_mov_b32_e32 v78, v81
	v_pk_add_f32 v[76:77], v[96:97], v[76:77]
	v_pk_add_f32 v[78:79], v[82:83], v[78:79]
	s_nop 0
	v_pk_add_f32 v[194:195], v[76:77], v[78:79]
	s_nop 0
	v_add_f32_e32 v3, v195, v194
	v_cmp_ngt_f32_e32 vcc, s65, v3
	s_cbranch_vccz .LBB0_1394
	ds_read_b128 v[76:79], v213
	ds_read_b128 v[80:83], v213 offset:64
	ds_read_b128 v[96:99], v213 offset:4352
	ds_read_b128 v[104:107], v213 offset:4416
	ds_read_b128 v[108:111], v213 offset:8704
	ds_read_b128 v[112:115], v213 offset:8768
	ds_read_b128 v[116:119], v213 offset:13056
	ds_read_b128 v[120:123], v213 offset:13120
	s_waitcnt lgkmcnt(7)
	v_mfma_f32_16x16x32_bf16 v[76:79], v[76:79], v[4:7], v[44:47]
	s_waitcnt lgkmcnt(6)
	v_mfma_f32_16x16x32_bf16 v[80:83], v[80:83], v[8:11], v[44:47]
	s_waitcnt lgkmcnt(5)
	v_mfma_f32_16x16x32_bf16 v[96:99], v[96:99], v[4:7], v[48:51]
	s_waitcnt lgkmcnt(4)
	v_mfma_f32_16x16x32_bf16 v[104:107], v[104:107], v[8:11], v[48:51]
	s_waitcnt lgkmcnt(3)
	v_mfma_f32_16x16x32_bf16 v[108:111], v[108:111], v[4:7], v[52:55]
	s_waitcnt lgkmcnt(2)
	v_mfma_f32_16x16x32_bf16 v[112:115], v[112:115], v[8:11], v[52:55]
	s_waitcnt lgkmcnt(1)
	v_mfma_f32_16x16x32_bf16 v[116:119], v[116:119], v[4:7], v[56:59]
	s_waitcnt lgkmcnt(0)
	v_mfma_f32_16x16x32_bf16 v[120:123], v[120:123], v[8:11], v[56:59]
	v_max3_f32 v3, v76, v80, s60
	v_max3_f32 v3, v3, v77, v81
	v_max3_f32 v3, v3, v78, v82
	v_max3_f32 v3, v3, v79, v83
	v_max3_f32 v3, v3, v96, v104
	v_max3_f32 v3, v3, v97, v105
	v_max3_f32 v3, v3, v98, v106
	v_max3_f32 v3, v3, v99, v107
	v_max3_f32 v3, v3, v108, v112
	v_max3_f32 v3, v3, v109, v113
	v_max3_f32 v3, v3, v110, v114
	v_max3_f32 v3, v3, v111, v115
	v_max3_f32 v3, v3, v116, v120
	v_max3_f32 v3, v3, v117, v121
	v_max3_f32 v3, v3, v118, v122
	v_max3_f32 v3, v3, v119, v123
	v_and_b32_e32 v125, 64, v198
	v_mov_b32_e32 v124, v3
	v_mov_b32_e32 v255, v3
	s_nop 1
	v_permlane16_swap_b32_e32 v124, v255
	s_waitcnt lgkmcnt(0)
	v_max_f32_e32 v3, v124, v255
	v_mov_b32_e32 v124, v3
	v_mov_b32_e32 v255, v3
	s_nop 1
	v_permlane32_swap_b32_e32 v124, v255
	s_waitcnt lgkmcnt(0)
; #define LAS __attribute__((address_space(3)))
; DI float fast_exp2(float x) { return __builtin_amdgcn_exp2f(x); }
; DI u32x2 tr4(const LAS unsigned char* p) { return __builtin_bit_cast(u32x2, __builtin_amdgcn_ds_read_tr16_b64_v4i16((LAS v4i16_t*)p)); }
; DI bf16x8 packp(f32x4 a, f32x4 b) { return __builtin_bit_cast(bf16x8, pack8(a, b)); }
; DI void at_pv(AtState& S, const f32x4 (&s1)[4], const f32x4 (&s2)[4], float alpha, float ps1, float ps2, const LAS unsigned char* buf, int hh, int fq, int tq, int tp) {
;     S.l1 = S.l1 * alpha + ps1; S.l2 = S.l2 * alpha + ps2;
; #pragma unroll
;     for (int dt = 0; dt < 4; ++dt) { S.O1[dt] = S.O1[dt] * alpha; S.O2[dt] = S.O2[dt] * alpha; }
;     bf16x8 p1[2], p2[2];
; #pragma unroll
;     for (int s = 0; s < 2; ++s) { p1[s] = packp(s1[2 * s], s1[2 * s + 1]); p2[s] = packp(s2[2 * s], s2[2 * s + 1]); }
; #pragma unroll
;     for (int dh = 0; dh < 2; ++dh) {
;         bf16x8 vt[2][2];
; #pragma unroll
;         for (int d2 = 0; d2 < 2; ++d2)
; #pragma unroll
;             for (int s = 0; s < 2; ++s) { const int dt = 2 * dh + d2; const LAS unsigned char* vr = buf + AT_V + (32 * s + 4 * fq + tq) * 288 + (hh * 64 + 16 * dt + 4 * tp) * 2; vt[d2][s] = cat44(tr4(vr), tr4(vr + 16 * 288)); }
; template <int VAR>
; DI void attn_tile(AtState& S, const LAS unsigned char* buf, const bf16x8 q1, const bf16x8 q2, int kt, bool diag, int qpos0, int qpos_l, float slope2, float adv, float decay, int hh, int fr, int fq) {
;     ...
;             const float bump = fmaxf(lm, 0.f);
;             const float alpha = decay * fast_exp2(-bump); S.ref += bump;
; #pragma unroll
;             for (int k4 = 0; k4 < 4; ++k4) { s1[k4] = s1[k4] - bump; s2[k4] = s2[k4] - bump; S.cinit[k4] = S.cinit[k4] - bump; }
;             at_exp(s1, s2, ps1, ps2);
;             at_pv(S, s1, s2, alpha, ps1, ps2, buf, hh, fq, tq, tp);
	v_max3_f32 v124, v255, v124, 0
	v_sub_f32_e32 v126, v79, v124
	v_sub_f32_e32 v127, v78, v124
	v_sub_f32_e32 v128, v77, v124
	v_sub_f32_e32 v129, v76, v124
	v_sub_f32_e32 v130, v83, v124
	v_sub_f32_e32 v131, v82, v124
	v_sub_f32_e32 v132, v81, v124
	v_sub_f32_e32 v133, v80, v124
	v_sub_f32_e32 v134, v99, v124
	v_sub_f32_e32 v135, v98, v124
	v_sub_f32_e32 v137, v97, v124
	v_sub_f32_e32 v138, v96, v124
	v_sub_f32_e32 v139, v107, v124
	v_sub_f32_e32 v151, v106, v124
	v_sub_f32_e32 v158, v105, v124
	v_sub_f32_e32 v159, v104, v124
	v_exp_f32_e32 v216, v129
	v_exp_f32_e32 v220, v133
	v_exp_f32_e32 v217, v128
	v_exp_f32_e32 v221, v132
	v_exp_f32_e32 v218, v127
	v_exp_f32_e32 v222, v131
	v_exp_f32_e32 v219, v126
	v_exp_f32_e32 v223, v130
	v_sub_f32_e32 v237, v111, v124
	v_sub_f32_e32 v236, v110, v124
	v_sub_f32_e32 v233, v109, v124
	v_sub_f32_e32 v232, v108, v124
	v_sub_f32_e32 v239, v115, v124
	v_sub_f32_e32 v238, v114, v124
	v_sub_f32_e32 v235, v113, v124
	v_sub_f32_e32 v234, v112, v124
	v_exp_f32_e32 v224, v138
	v_exp_f32_e32 v226, v159
	v_exp_f32_e32 v225, v137
	v_exp_f32_e32 v227, v158
	v_exp_f32_e32 v228, v135
	v_exp_f32_e32 v230, v151
	v_exp_f32_e32 v229, v134
	v_exp_f32_e32 v231, v139
	v_sub_f32_e32 v119, v119, v124
	v_sub_f32_e32 v118, v118, v124
	v_sub_f32_e32 v117, v117, v124
	v_sub_f32_e32 v116, v116, v124
	v_sub_f32_e32 v123, v123, v124
	v_sub_f32_e32 v122, v122, v124
	v_sub_f32_e32 v121, v121, v124
	v_sub_f32_e32 v120, v120, v124
	v_exp_f32_e32 v232, v232
	v_exp_f32_e32 v234, v234
	v_exp_f32_e32 v233, v233
	v_exp_f32_e32 v235, v235
	v_exp_f32_e32 v236, v236
	v_exp_f32_e32 v238, v238
	v_exp_f32_e32 v237, v237
	v_exp_f32_e32 v239, v239
	v_exp_f32_e32 v240, v116
	v_exp_f32_e32 v242, v120
	v_exp_f32_e32 v241, v117
	v_exp_f32_e32 v243, v121
	v_exp_f32_e32 v244, v118
	v_exp_f32_e32 v246, v122
	v_exp_f32_e32 v245, v119
	v_exp_f32_e32 v247, v123
	v_pk_add_f32 v[110:111], v[228:229], v[218:219]
	v_pk_add_f32 v[108:109], v[224:225], v[216:217]
	v_pk_add_f32 v[114:115], v[230:231], v[222:223]
	v_pk_add_f32 v[112:113], v[226:227], v[220:221]
	v_pk_add_f32 v[108:109], v[232:233], v[108:109]
	v_pk_add_f32 v[110:111], v[236:237], v[110:111]
	v_pk_add_f32 v[112:113], v[234:235], v[112:113]
	v_pk_add_f32 v[114:115], v[238:239], v[114:115]
	v_pk_add_f32 v[110:111], v[244:245], v[110:111]
	v_pk_add_f32 v[108:109], v[240:241], v[108:109]
	v_pk_add_f32 v[114:115], v[246:247], v[114:115]
	v_pk_add_f32 v[112:113], v[242:243], v[112:113]
	v_cvt_pk_bf16_f32 v216, v216, v217
	v_cvt_pk_bf16_f32 v217, v218, v219
	v_cvt_pk_bf16_f32 v218, v224, v225
	v_cvt_pk_bf16_f32 v219, v228, v229
	v_cvt_pk_bf16_f32 v220, v220, v221
	v_cvt_pk_bf16_f32 v221, v222, v223
	v_cvt_pk_bf16_f32 v222, v226, v227
	v_cvt_pk_bf16_f32 v223, v230, v231
	v_cvt_pk_bf16_f32 v224, v232, v233
	v_cvt_pk_bf16_f32 v225, v236, v237
	v_cvt_pk_bf16_f32 v226, v240, v241
	v_cvt_pk_bf16_f32 v227, v244, v245
	v_cvt_pk_bf16_f32 v228, v234, v235
	v_cvt_pk_bf16_f32 v229, v238, v239
	v_cvt_pk_bf16_f32 v230, v242, v243
	v_cvt_pk_bf16_f32 v231, v246, v247
	ds_read_b64_tr_b16 v[232:233], v208 offset:17408
	ds_read_b64_tr_b16 v[236:237], v208 offset:17440
	ds_read_b64_tr_b16 v[234:235], v208 offset:22016
	ds_read_b64_tr_b16 v[240:241], v208 offset:26624
	ds_read_b64_tr_b16 v[242:243], v208 offset:31232
	ds_read_b64_tr_b16 v[238:239], v208 offset:22048
	ds_read_b64_tr_b16 v[244:245], v208 offset:26656
	ds_read_b64_tr_b16 v[246:247], v208 offset:31264
	v_exp_f32_e64 v125, -v124
	v_mov_b32_e32 v116, v112
	v_mov_b32_e32 v117, v108
	v_mov_b32_e32 v108, v113
	v_mov_b32_e32 v112, v114
	v_mov_b32_e32 v113, v110
	v_mov_b32_e32 v110, v115
	v_pk_add_f32 v[108:109], v[116:117], v[108:109]
	v_pk_add_f32 v[110:111], v[112:113], v[110:111]
	v_mul_f32_e32 v136, v150, v125
	v_pk_add_f32 v[108:109], v[108:109], v[110:111]
	v_add_f32_e32 v3, v215, v124
	v_sub_f32_e32 v79, v47, v124
	v_sub_f32_e32 v78, v46, v124
	v_sub_f32_e32 v77, v45, v124
	v_sub_f32_e32 v76, v44, v124
	v_sub_f32_e32 v99, v51, v124
	v_sub_f32_e32 v98, v50, v124
	v_sub_f32_e32 v97, v49, v124
	v_sub_f32_e32 v96, v48, v124
	v_sub_f32_e32 v107, v55, v124
	v_sub_f32_e32 v106, v54, v124
	v_sub_f32_e32 v105, v53, v124
	v_sub_f32_e32 v104, v52, v124
	v_sub_f32_e32 v83, v59, v124
	v_sub_f32_e32 v82, v58, v124
	v_sub_f32_e32 v81, v57, v124
	v_sub_f32_e32 v80, v56, v124
	v_pk_fma_f32 v[158:159], v[156:157], v[136:137], v[108:109] op_sel_hi:[1,0,1]
	v_pk_mul_f32 v[110:111], v[66:67], v[136:137] op_sel_hi:[1,0]
	v_pk_mul_f32 v[108:109], v[64:65], v[136:137] op_sel_hi:[1,0]
	v_pk_mul_f32 v[114:115], v[74:75], v[136:137] op_sel_hi:[1,0]
	v_pk_mul_f32 v[112:113], v[72:73], v[136:137] op_sel_hi:[1,0]
	v_pk_mul_f32 v[118:119], v[62:63], v[136:137] op_sel_hi:[1,0]
	v_pk_mul_f32 v[116:117], v[60:61], v[136:137] op_sel_hi:[1,0]
	v_pk_mul_f32 v[122:123], v[70:71], v[136:137] op_sel_hi:[1,0]
	v_pk_mul_f32 v[120:121], v[68:69], v[136:137] op_sel_hi:[1,0]
	v_pk_mul_f32 v[126:127], v[90:91], v[136:137] op_sel_hi:[1,0]
	v_pk_mul_f32 v[124:125], v[88:89], v[136:137] op_sel_hi:[1,0]
	v_pk_mul_f32 v[130:131], v[102:103], v[136:137] op_sel_hi:[1,0]
	v_pk_mul_f32 v[128:129], v[100:101], v[136:137] op_sel_hi:[1,0]
	v_pk_mul_f32 v[134:135], v[86:87], v[136:137] op_sel_hi:[1,0]
	v_pk_mul_f32 v[132:133], v[84:85], v[136:137] op_sel_hi:[1,0]
	v_pk_mul_f32 v[138:139], v[94:95], v[136:137] op_sel_hi:[1,0]
	v_pk_mul_f32 v[136:137], v[92:93], v[136:137] op_sel_hi:[1,0]
	s_waitcnt lgkmcnt(5)
	v_mfma_f32_16x16x32_bf16 v[108:111], v[232:235], v[216:219], v[108:111]
	v_mfma_f32_16x16x32_bf16 v[112:115], v[232:235], v[220:223], v[112:115]
	s_waitcnt lgkmcnt(2)
; #define LAS __attribute__((address_space(3)))
; #define MFMA16(a, b, c) __builtin_amdgcn_mfma_f32_16x16x32_bf16((a), (b), (c), 0, 0, 0)
; DI u32x2 tr4(const LAS unsigned char* p) { return __builtin_bit_cast(u32x2, __builtin_amdgcn_ds_read_tr16_b64_v4i16((LAS v4i16_t*)p)); }
; DI bf16x8 packp(f32x4 a, f32x4 b) { return __builtin_bit_cast(bf16x8, pack8(a, b)); }
; DI void at_pv(AtState& S, const f32x4 (&s1)[4], const f32x4 (&s2)[4], float alpha, float ps1, float ps2, const LAS unsigned char* buf, int hh, int fq, int tq, int tp) {
;     S.l1 = S.l1 * alpha + ps1; S.l2 = S.l2 * alpha + ps2;
; #pragma unroll
;     for (int dt = 0; dt < 4; ++dt) { S.O1[dt] = S.O1[dt] * alpha; S.O2[dt] = S.O2[dt] * alpha; }
;     bf16x8 p1[2], p2[2];
; #pragma unroll
;     for (int s = 0; s < 2; ++s) { p1[s] = packp(s1[2 * s], s1[2 * s + 1]); p2[s] = packp(s2[2 * s], s2[2 * s + 1]); }
; #pragma unroll
;     for (int dh = 0; dh < 2; ++dh) {
;         bf16x8 vt[2][2];
; #pragma unroll
;         for (int d2 = 0; d2 < 2; ++d2)
; #pragma unroll
;             for (int s = 0; s < 2; ++s) { const int dt = 2 * dh + d2; const LAS unsigned char* vr = buf + AT_V + (32 * s + 4 * fq + tq) * 288 + (hh * 64 + 16 * dt + 4 * tp) * 2; vt[d2][s] = cat44(tr4(vr), tr4(vr + 16 * 288)); }
;         __builtin_amdgcn_s_setprio(1);
; #pragma unroll
;         for (int s = 0; s < 2; ++s)
; #pragma unroll
;             for (int d2 = 0; d2 < 2; ++d2) { const int dt = 2 * dh + d2; S.O1[dt] = MFMA16(vt[d2][s], p1[s], S.O1[dt]); S.O2[dt] = MFMA16(vt[d2][s], p2[s], S.O2[dt]); }
;         __builtin_amdgcn_s_setprio(0);
;         __builtin_amdgcn_sched_barrier(0);
;     }
; template <int VAR>
; DI void attn_tile(AtState& S, const LAS unsigned char* buf, const bf16x8 q1, const bf16x8 q2, int kt, bool diag, int qpos0, int qpos_l, float slope2, float adv, float decay, int hh, int fr, int fq) {
;     ...
;         } else {
;             asm volatile("; attention: fast tail" ::: "memory");
;             at_pv(S, s1, s2, decay, ps1, ps2, buf, hh, fq, tq, tp);
	v_mfma_f32_16x16x32_bf16 v[232:235], v[236:239], v[216:219], v[116:119]
	v_mfma_f32_16x16x32_bf16 v[236:239], v[236:239], v[220:223], v[120:123]
	v_mfma_f32_16x16x32_bf16 v[120:123], v[240:243], v[224:227], v[108:111]
	v_mfma_f32_16x16x32_bf16 v[116:119], v[240:243], v[228:231], v[112:115]
	s_waitcnt lgkmcnt(0)
	v_mfma_f32_16x16x32_bf16 v[112:115], v[244:247], v[224:227], v[232:235]
	v_mfma_f32_16x16x32_bf16 v[108:111], v[244:247], v[228:231], v[236:239]
	s_nop 0
	ds_read_b64_tr_b16 v[232:233], v208 offset:17472
	ds_read_b64_tr_b16 v[236:237], v208 offset:17504
	ds_read_b64_tr_b16 v[234:235], v208 offset:22080
	ds_read_b64_tr_b16 v[238:239], v208 offset:22112
	ds_read_b64_tr_b16 v[240:241], v208 offset:26688
	ds_read_b64_tr_b16 v[242:243], v208 offset:31296
	ds_read_b64_tr_b16 v[246:247], v208 offset:31328
	ds_read_b64_tr_b16 v[244:245], v208 offset:26720
	s_waitcnt lgkmcnt(5)
	v_mfma_f32_16x16x32_bf16 v[124:127], v[232:235], v[216:219], v[124:127]
	v_mfma_f32_16x16x32_bf16 v[128:131], v[232:235], v[220:223], v[128:131]
	s_waitcnt lgkmcnt(4)
	v_mfma_f32_16x16x32_bf16 v[216:219], v[236:239], v[216:219], v[132:135]
	v_mfma_f32_16x16x32_bf16 v[220:223], v[236:239], v[220:223], v[136:139]
	s_waitcnt lgkmcnt(2)
	v_mfma_f32_16x16x32_bf16 v[136:139], v[240:243], v[224:227], v[124:127]
	v_mfma_f32_16x16x32_bf16 v[132:135], v[240:243], v[228:231], v[128:131]
	s_waitcnt lgkmcnt(0)
	v_mfma_f32_16x16x32_bf16 v[128:131], v[244:247], v[224:227], v[216:219]
	v_mfma_f32_16x16x32_bf16 v[124:127], v[244:247], v[228:231], v[220:223]
	s_cbranch_execnz .LBB0_1380
.LBB0_1379:
	v_cvt_pk_bf16_f32 v216, v164, v165
	v_cvt_pk_bf16_f32 v219, v176, v177
	v_cvt_pk_bf16_f32 v165, v174, v175
	ds_read_b64_tr_b16 v[108:109], v208 offset:17408
	ds_read_b64_tr_b16 v[112:113], v208 offset:17440
	ds_read_b64_tr_b16 v[110:111], v208 offset:22016
	ds_read_b64_tr_b16 v[116:117], v208 offset:26624
	ds_read_b64_tr_b16 v[118:119], v208 offset:31232
	ds_read_b64_tr_b16 v[114:115], v208 offset:22048
	ds_read_b64_tr_b16 v[174:175], v208 offset:26656
	ds_read_b64_tr_b16 v[176:177], v208 offset:31264
	v_mov_b32_e32 v151, v150
	v_pk_fma_f32 v[158:159], v[154:155], v[156:157], v[194:195]
	v_pk_mul_f32 v[78:79], v[150:151], v[66:67]
	v_pk_mul_f32 v[76:77], v[152:153], v[64:65]
	v_pk_mul_f32 v[82:83], v[150:151], v[74:75]
	v_pk_mul_f32 v[80:81], v[152:153], v[72:73]
	v_pk_mul_f32 v[98:99], v[150:151], v[62:63]
	v_pk_mul_f32 v[96:97], v[152:153], v[60:61]
	v_pk_mul_f32 v[106:107], v[150:151], v[70:71]
	v_pk_mul_f32 v[104:105], v[152:153], v[68:69]
	v_pk_mul_f32 v[126:127], v[150:151], v[90:91]
	v_pk_mul_f32 v[124:125], v[152:153], v[88:89]
	v_pk_mul_f32 v[130:131], v[150:151], v[102:103]
	v_pk_mul_f32 v[128:129], v[152:153], v[100:101]
	v_pk_mul_f32 v[134:135], v[150:151], v[86:87]
	v_pk_mul_f32 v[132:133], v[152:153], v[84:85]
	v_pk_mul_f32 v[138:139], v[150:151], v[94:95]
	v_pk_mul_f32 v[136:137], v[152:153], v[92:93]
	v_cvt_pk_bf16_f32 v217, v168, v169
	v_cvt_pk_bf16_f32 v218, v172, v173
	v_cvt_pk_bf16_f32 v162, v162, v163
	v_cvt_pk_bf16_f32 v163, v166, v167
	v_cvt_pk_bf16_f32 v164, v170, v171
	v_cvt_pk_bf16_f32 v166, v180, v181
	v_cvt_pk_bf16_f32 v167, v184, v185
	v_cvt_pk_bf16_f32 v168, v188, v189
	v_cvt_pk_bf16_f32 v169, v192, v193
	v_cvt_pk_bf16_f32 v170, v178, v179
	v_cvt_pk_bf16_f32 v171, v182, v183
	v_cvt_pk_bf16_f32 v172, v186, v187
	v_cvt_pk_bf16_f32 v173, v190, v191
	s_waitcnt lgkmcnt(5)
	v_mfma_f32_16x16x32_bf16 v[76:79], v[108:111], v[216:219], v[76:79]
	v_mfma_f32_16x16x32_bf16 v[80:83], v[108:111], v[162:165], v[80:83]
	s_waitcnt lgkmcnt(2)
	v_mfma_f32_16x16x32_bf16 v[96:99], v[112:115], v[216:219], v[96:99]
	v_mfma_f32_16x16x32_bf16 v[104:107], v[112:115], v[162:165], v[104:107]
	v_mfma_f32_16x16x32_bf16 v[120:123], v[116:119], v[166:169], v[76:79]
	v_mfma_f32_16x16x32_bf16 v[116:119], v[116:119], v[170:173], v[80:83]
	s_waitcnt lgkmcnt(0)
	v_mfma_f32_16x16x32_bf16 v[112:115], v[174:177], v[166:169], v[96:99]
	v_mfma_f32_16x16x32_bf16 v[108:111], v[174:177], v[170:173], v[104:107]
	s_waitcnt vmcnt(4)
	ds_write_b128 v143, v[12:15] offset:35840
	ds_write_b128 v202, v[16:19] offset:53248
	ds_write_b128 v203, v[20:23] offset:35840
	ds_write_b128 v204, v[24:27] offset:53248
	ds_read_b64_tr_b16 v[76:77], v208 offset:17472
	ds_read_b64_tr_b16 v[80:81], v208 offset:17504
	ds_read_b64_tr_b16 v[78:79], v208 offset:22080
	ds_read_b64_tr_b16 v[82:83], v208 offset:22112
	ds_read_b64_tr_b16 v[96:97], v208 offset:26688
	ds_read_b64_tr_b16 v[98:99], v208 offset:31296
	ds_read_b64_tr_b16 v[106:107], v208 offset:31328
	ds_read_b64_tr_b16 v[104:105], v208 offset:26720
	s_waitcnt lgkmcnt(5)
	v_mfma_f32_16x16x32_bf16 v[124:127], v[76:79], v[216:219], v[124:127]
	v_mfma_f32_16x16x32_bf16 v[76:79], v[76:79], v[162:165], v[128:131]
	s_waitcnt lgkmcnt(4)
	v_mfma_f32_16x16x32_bf16 v[128:131], v[80:83], v[216:219], v[132:135]
	v_mfma_f32_16x16x32_bf16 v[80:83], v[80:83], v[162:165], v[136:139]
	s_waitcnt lgkmcnt(2)
	v_mfma_f32_16x16x32_bf16 v[136:139], v[96:99], v[166:169], v[124:127]
	v_mfma_f32_16x16x32_bf16 v[132:135], v[96:99], v[170:173], v[76:79]
	s_waitcnt lgkmcnt(0)
	v_mfma_f32_16x16x32_bf16 v[128:131], v[104:107], v[166:169], v[128:131]
	v_mfma_f32_16x16x32_bf16 v[124:127], v[104:107], v[170:173], v[80:83]
	s_nop 1
	v_mov_b64_e32 v[82:83], v[58:59]
	v_mov_b64_e32 v[78:79], v[46:47]
	v_mov_b64_e32 v[98:99], v[50:51]
	v_mov_b64_e32 v[106:107], v[54:55]
	v_mov_b32_e32 v3, v215
	v_mov_b64_e32 v[80:81], v[56:57]
	v_mov_b64_e32 v[76:77], v[44:45]
	v_mov_b64_e32 v[96:97], v[48:49]
	v_mov_b64_e32 v[104:105], v[52:53]
	s_mov_b64 s[18:19], 0
	s_branch .Lcommit_done_A

; #define LAS __attribute__((address_space(3)))
; DI float fast_exp2(float x) { return __builtin_amdgcn_exp2f(x); }
; #define MFMA16(a, b, c) __builtin_amdgcn_mfma_f32_16x16x32_bf16((a), (b), (c), 0, 0, 0)
; DI bf16x8 packp(f32x4 a, f32x4 b) { return __builtin_bit_cast(bf16x8, pack8(a, b)); }
; DI void at_pv(AtState& S, const f32x4 (&s1)[4], const f32x4 (&s2)[4], float alpha, float ps1, float ps2, const LAS unsigned char* buf, int hh, int fq, int tq, int tp) {
;     S.l1 = S.l1 * alpha + ps1; S.l2 = S.l2 * alpha + ps2;
; #pragma unroll
;     for (int dt = 0; dt < 4; ++dt) { S.O1[dt] = S.O1[dt] * alpha; S.O2[dt] = S.O2[dt] * alpha; }
;     bf16x8 p1[2], p2[2];
; #pragma unroll
;     for (int s = 0; s < 2; ++s) { p1[s] = packp(s1[2 * s], s1[2 * s + 1]); p2[s] = packp(s2[2 * s], s2[2 * s + 1]); }
; #pragma unroll
;     for (int dh = 0; dh < 2; ++dh) {
;         bf16x8 vt[2][2];
; #pragma unroll
;         for (int d2 = 0; d2 < 2; ++d2)
; #pragma unroll
;             for (int s = 0; s < 2; ++s) { const int dt = 2 * dh + d2; const LAS unsigned char* vr = buf + AT_V + (32 * s + 4 * fq + tq) * 288 + (hh * 64 + 16 * dt + 4 * tp) * 2; vt[d2][s] = cat44(tr4(vr), tr4(vr + 16 * 288)); }
;         __builtin_amdgcn_s_setprio(1);
; #pragma unroll
;         for (int s = 0; s < 2; ++s)
; #pragma unroll
;             for (int d2 = 0; d2 < 2; ++d2) { const int dt = 2 * dh + d2; S.O1[dt] = MFMA16(vt[d2][s], p1[s], S.O1[dt]); S.O2[dt] = MFMA16(vt[d2][s], p2[s], S.O2[dt]); }
;         __builtin_amdgcn_s_setprio(0);
;         __builtin_amdgcn_sched_barrier(0);
;     }
; template <int VAR>
; DI void attn_tile(AtState& S, const LAS unsigned char* buf, const bf16x8 q1, const bf16x8 q2, int kt, bool diag, int qpos0, int qpos_l, float slope2, float adv, float decay, int hh, int fr, int fq) {
;     ...
;         const float nref = fmaxf(S.ref, mx);
;         const float alpha = fast_exp2(S.ref - nref); S.ref = nref;
; #pragma unroll
;         for (int k4 = 0; k4 < 4; ++k4) { s1[k4] = s1[k4] - nref; s2[k4] = s2[k4] - nref; }
;         if (kt == 0) { const float c0 = -slope2 * (float)qpos0 - S.ref;
; #pragma unroll
;             for (int k4 = 0; k4 < 4; ++k4)
; #pragma unroll
;                 for (int j = 0; j < 4; ++j) S.cinit[k4][j] = slope2 * (float)(16 * k4 + j - ql) + c0; }
;         at_exp(s1, s2, ps1, ps2);
;         at_pv(S, s1, s2, alpha, ps1, ps2, buf, hh, fq, tq, tp);
.LBB0_1384:
	v_sub_f32_e32 v77, v125, v3
	v_sub_f32_e32 v83, v123, v3
	v_sub_f32_e32 v97, v121, v3
	v_sub_f32_e32 v98, v118, v3
	v_sub_f32_e32 v109, v124, v3
	v_sub_f32_e32 v108, v122, v3
	v_sub_f32_e32 v110, v120, v3
	v_sub_f32_e32 v99, v119, v3
	v_sub_f32_e32 v113, v133, v3
	v_sub_f32_e32 v114, v131, v3
	v_sub_f32_e32 v111, v129, v3
	v_sub_f32_e32 v112, v127, v3
	v_sub_f32_e32 v117, v132, v3
	v_sub_f32_e32 v116, v130, v3
	v_sub_f32_e32 v118, v128, v3
	v_sub_f32_e32 v115, v126, v3
	v_sub_f32_e32 v124, v107, v3
	v_sub_f32_e32 v125, v106, v3
	v_sub_f32_e32 v121, v105, v3
	v_sub_f32_e32 v126, v104, v3
	v_exp_f32_e32 v98, v98
	v_exp_f32_e32 v104, v99
	v_exp_f32_e32 v99, v97
	v_exp_f32_e32 v105, v110
	v_exp_f32_e32 v106, v83
	v_exp_f32_e32 v107, v77
	v_exp_f32_e32 v108, v108
	v_exp_f32_e32 v109, v109
	v_sub_f32_e32 v123, v137, v3
	v_sub_f32_e32 v122, v136, v3
	v_sub_f32_e32 v119, v135, v3
	v_sub_f32_e32 v120, v134, v3
	v_exp_f32_e32 v110, v112
	v_exp_f32_e32 v112, v115
	v_exp_f32_e32 v111, v111
	v_exp_f32_e32 v114, v114
	v_exp_f32_e32 v115, v113
	v_exp_f32_e32 v116, v116
	v_exp_f32_e32 v117, v117
	v_exp_f32_e32 v113, v118
	v_sub_f32_e32 v127, v82, v3
	v_sub_f32_e32 v131, v151, v3
	v_sub_f32_e32 v132, v139, v3
	v_sub_f32_e32 v130, v138, v3
	v_sub_f32_e32 v133, v79, v3
	v_sub_f32_e32 v134, v78, v3
	v_sub_f32_e32 v135, v81, v3
	v_sub_f32_e32 v136, v80, v3
	v_exp_f32_e32 v118, v120
	v_exp_f32_e32 v120, v126
	v_exp_f32_e32 v119, v119
	v_exp_f32_e32 v121, v121
	v_exp_f32_e32 v122, v122
	v_exp_f32_e32 v123, v123
	v_exp_f32_e32 v128, v125
	v_exp_f32_e32 v129, v124
	v_sub_f32_e32 v76, v214, v3
	v_exp_f32_e32 v124, v130
	v_exp_f32_e32 v130, v136
	v_exp_f32_e32 v125, v132
	v_exp_f32_e32 v126, v131
	v_exp_f32_e32 v127, v127
	v_exp_f32_e32 v132, v134
	v_exp_f32_e32 v133, v133
	v_exp_f32_e32 v131, v135
	v_exp_f32_e32 v96, v76
	v_pk_add_f32 v[78:79], v[114:115], v[106:107]
	v_pk_add_f32 v[76:77], v[110:111], v[98:99]
	v_pk_add_f32 v[82:83], v[116:117], v[108:109]
	v_pk_add_f32 v[80:81], v[112:113], v[104:105]
	v_pk_add_f32 v[76:77], v[118:119], v[76:77]
	v_pk_add_f32 v[78:79], v[122:123], v[78:79]
	v_pk_add_f32 v[80:81], v[120:121], v[80:81]
	v_pk_add_f32 v[82:83], v[128:129], v[82:83]
	v_pk_add_f32 v[78:79], v[126:127], v[78:79]
	v_pk_add_f32 v[76:77], v[124:125], v[76:77]
	v_pk_add_f32 v[82:83], v[132:133], v[82:83]
	v_pk_add_f32 v[80:81], v[130:131], v[80:81]
	v_mov_b32_e32 v135, v76
	v_mov_b32_e32 v134, v80
	v_mov_b32_e32 v76, v81
	v_mov_b32_e32 v80, v82
	v_mov_b32_e32 v81, v78
	v_mov_b32_e32 v78, v83
	v_pk_add_f32 v[76:77], v[134:135], v[76:77]
	v_pk_add_f32 v[78:79], v[80:81], v[78:79]
	v_pk_mul_f32 v[66:67], v[66:67], v[96:97] op_sel_hi:[1,0]
	v_pk_add_f32 v[76:77], v[76:77], v[78:79]
	v_pk_mul_f32 v[64:65], v[64:65], v[96:97] op_sel_hi:[1,0]
	v_pk_fma_f32 v[158:159], v[156:157], v[96:97], v[76:77] op_sel_hi:[1,0,1]
	v_pk_mul_f32 v[74:75], v[74:75], v[96:97] op_sel_hi:[1,0]
	v_pk_mul_f32 v[72:73], v[72:73], v[96:97] op_sel_hi:[1,0]
	v_pk_mul_f32 v[62:63], v[62:63], v[96:97] op_sel_hi:[1,0]
	v_pk_mul_f32 v[60:61], v[60:61], v[96:97] op_sel_hi:[1,0]
	v_pk_mul_f32 v[70:71], v[70:71], v[96:97] op_sel_hi:[1,0]
	v_pk_mul_f32 v[68:69], v[68:69], v[96:97] op_sel_hi:[1,0]
	v_pk_mul_f32 v[78:79], v[90:91], v[96:97] op_sel_hi:[1,0]
	v_pk_mul_f32 v[76:77], v[88:89], v[96:97] op_sel_hi:[1,0]
	v_pk_mul_f32 v[82:83], v[102:103], v[96:97] op_sel_hi:[1,0]
	v_pk_mul_f32 v[80:81], v[100:101], v[96:97] op_sel_hi:[1,0]
	v_pk_mul_f32 v[86:87], v[86:87], v[96:97] op_sel_hi:[1,0]
	v_pk_mul_f32 v[84:85], v[84:85], v[96:97] op_sel_hi:[1,0]
	v_pk_mul_f32 v[90:91], v[94:95], v[96:97] op_sel_hi:[1,0]
	v_pk_mul_f32 v[88:89], v[92:93], v[96:97] op_sel_hi:[1,0]
	v_cvt_pk_bf16_f32 v92, v98, v99
	v_cvt_pk_bf16_f32 v93, v106, v107
	v_cvt_pk_bf16_f32 v94, v110, v111
	v_cvt_pk_bf16_f32 v95, v114, v115
	v_cvt_pk_bf16_f32 v96, v104, v105
	v_cvt_pk_bf16_f32 v97, v108, v109
	v_cvt_pk_bf16_f32 v98, v112, v113
	v_cvt_pk_bf16_f32 v102, v124, v125
	v_cvt_pk_bf16_f32 v103, v126, v127
	ds_read_b64_tr_b16 v[104:105], v208 offset:17408
	ds_read_b64_tr_b16 v[108:109], v208 offset:17440
	ds_read_b64_tr_b16 v[106:107], v208 offset:22016
	ds_read_b64_tr_b16 v[110:111], v208 offset:22048
	ds_read_b64_tr_b16 v[112:113], v208 offset:26624
	ds_read_b64_tr_b16 v[114:115], v208 offset:31232
	ds_read_b64_tr_b16 v[126:127], v208 offset:31264
	ds_read_b64_tr_b16 v[124:125], v208 offset:26656
	v_cvt_pk_bf16_f32 v99, v116, v117
	v_cvt_pk_bf16_f32 v100, v118, v119
	v_cvt_pk_bf16_f32 v101, v122, v123
	v_cvt_pk_bf16_f32 v162, v120, v121
	v_cvt_pk_bf16_f32 v163, v128, v129
	v_cvt_pk_bf16_f32 v164, v130, v131
	v_cvt_pk_bf16_f32 v165, v132, v133
	s_waitcnt lgkmcnt(5)
	v_mfma_f32_16x16x32_bf16 v[64:67], v[104:107], v[92:95], v[64:67]
	v_mfma_f32_16x16x32_bf16 v[72:75], v[104:107], v[96:99], v[72:75]
	s_waitcnt lgkmcnt(4)
	v_mfma_f32_16x16x32_bf16 v[60:63], v[108:111], v[92:95], v[60:63]
	v_mfma_f32_16x16x32_bf16 v[68:71], v[108:111], v[96:99], v[68:71]
	s_waitcnt lgkmcnt(2)
	v_mfma_f32_16x16x32_bf16 v[120:123], v[112:115], v[100:103], v[64:67]
	v_mfma_f32_16x16x32_bf16 v[116:119], v[112:115], v[162:165], v[72:75]
	s_waitcnt lgkmcnt(0)
	v_mfma_f32_16x16x32_bf16 v[112:115], v[124:127], v[100:103], v[60:63]
	v_mfma_f32_16x16x32_bf16 v[108:111], v[124:127], v[162:165], v[68:71]
	s_nop 0
	ds_read_b64_tr_b16 v[60:61], v208 offset:17472
	ds_read_b64_tr_b16 v[64:65], v208 offset:17504
	ds_read_b64_tr_b16 v[62:63], v208 offset:22080
	ds_read_b64_tr_b16 v[66:67], v208 offset:22112
	ds_read_b64_tr_b16 v[68:69], v208 offset:26688
	ds_read_b64_tr_b16 v[70:71], v208 offset:31296
	ds_read_b64_tr_b16 v[74:75], v208 offset:31328
	ds_read_b64_tr_b16 v[72:73], v208 offset:26720
	s_waitcnt lgkmcnt(5)
	v_mfma_f32_16x16x32_bf16 v[76:79], v[60:63], v[92:95], v[76:79]
	v_mfma_f32_16x16x32_bf16 v[60:63], v[60:63], v[96:99], v[80:83]
	s_waitcnt lgkmcnt(4)
	v_mfma_f32_16x16x32_bf16 v[80:83], v[64:67], v[92:95], v[84:87]
	v_mfma_f32_16x16x32_bf16 v[64:67], v[64:67], v[96:99], v[88:91]
	s_waitcnt lgkmcnt(2)
	v_mfma_f32_16x16x32_bf16 v[136:139], v[68:71], v[100:103], v[76:79]
	v_mfma_f32_16x16x32_bf16 v[132:135], v[68:71], v[162:165], v[60:63]
	s_waitcnt lgkmcnt(0)
	v_mfma_f32_16x16x32_bf16 v[128:131], v[72:75], v[100:103], v[80:83]
	v_mfma_f32_16x16x32_bf16 v[124:127], v[72:75], v[162:165], v[64:67]
	s_nop 0
	v_mov_b64_e32 v[82:83], v[58:59]
	v_mov_b64_e32 v[78:79], v[46:47]
	v_mov_b64_e32 v[98:99], v[50:51]
	v_mov_b64_e32 v[106:107], v[54:55]
	v_mov_b64_e32 v[80:81], v[56:57]
	v_mov_b64_e32 v[76:77], v[44:45]
	v_mov_b64_e32 v[96:97], v[48:49]
	v_mov_b64_e32 v[104:105], v[52:53]

; DI void lds_barrier() { asm volatile("s_waitcnt lgkmcnt(0)" ::: "memory"); __builtin_amdgcn_s_barrier(); asm volatile("" ::: "memory"); }
; template <int VAR>
; DI void attn_tile(AtState& S, const LAS unsigned char* buf, const bf16x8 q1, const bf16x8 q2, int kt, bool diag, int qpos0, int qpos_l, float slope2, float adv, float decay, int hh, int fr, int fq) {
;     ...
;         asm volatile("; attention: fast tile" ::: "memory");
;         at_qk(s1, s2, buf, q1, q2, S.cinit, hh, fr, fq);
;         S.ref += adv;
;         at_exp(s1, s2, ps1, ps2);
;         if (__any(!(ps1 + ps2 < 0x1p60f))) {
;             asm volatile("; attention: bump" ::: "memory");
;             at_qk(s1, s2, buf, q1, q2, S.cinit, hh, fr, fq);
;             float lm = -1e30f;
; #pragma unroll
;             for (int k4 = 0; k4 < 4; ++k4)
; #pragma unroll
;                 for (int j = 0; j < 4; ++j) lm = fmaxf(lm, fmaxf(s1[k4][j], s2[k4][j]));
;             lm = fmaxf(lm, __shfl_xor(lm, 16)); lm = fmaxf(lm, __shfl_xor(lm, 32));
; template <int VAR>
; DI void attn_segment(const Args& a, const Frame& F, int l, int qrow0, int qpos0, int hp, int ntile, int nf32, const float* ck, const float* cv, int prow0) {
;     ...
;             lds_barrier();
;             if (kt + 1 >= ntile) break;
;             atb_issue(ra, pb + (size_t)(kt + 3 < nl ? kt + 3 : nl) * TSTR, voff);
;             attn_tile<VAR>(S, F.lds + ((kt + 1) & 1) * AT_BUF, q1, q2, kt + 1, kt + 2 == ntile, qpos0, qpos_l, slope2, adv, decay, hh, fr, fq);
.Lcommit_done_A:
	s_waitcnt lgkmcnt(0)
	s_barrier
	s_add_i32 s14, s26, -2
	s_cmp_ge_i32 s14, s24
	s_mov_b64 s[14:15], -1
	s_cbranch_scc1 .LBB0_1375
	s_min_i32 s14, s26, s25
	s_ashr_i32 s15, s14, 31
	s_lshl_b64 s[14:15], s[14:15], 18
	s_add_u32 s14, s0, s14
	s_addc_u32 s15, s1, s15
	v_lshl_add_u64 v[16:17], s[14:15], 0, v[144:145]
	v_lshl_add_u64 v[24:25], s[14:15], 0, v[146:147]
	global_load_dwordx4 v[12:15], v[16:17], off offset:1024
	s_nop 0
	global_load_dwordx4 v[16:19], v[16:17], off offset:1536
	s_nop 0
	global_load_dwordx4 v[20:23], v[24:25], off offset:1024
	s_nop 0
	global_load_dwordx4 v[24:27], v[24:25], off offset:1536
	s_cmpk_lg_i32 s28, 0x41
	s_mov_b64 s[14:15], -1
	s_cbranch_scc0 .LBB0_1391
	ds_read_b128 v[44:47], v213 offset:35840
	ds_read_b128 v[48:51], v213 offset:35904
	ds_read_b128 v[52:55], v213 offset:40192
	ds_read_b128 v[56:59], v213 offset:40256
	ds_read_b128 v[60:63], v213 offset:44544
	ds_read_b128 v[64:67], v213 offset:44608
	ds_read_b128 v[68:71], v213 offset:48896
	ds_read_b128 v[72:75], v213 offset:48960
	s_waitcnt lgkmcnt(7)
	v_mfma_f32_16x16x32_bf16 v[44:47], v[44:47], v[4:7], v[76:79]
	v_add_f32_e32 v215, v205, v3
	s_waitcnt lgkmcnt(6)
	v_mfma_f32_16x16x32_bf16 v[48:51], v[48:51], v[8:11], v[76:79]
	s_waitcnt lgkmcnt(5)
	v_mfma_f32_16x16x32_bf16 v[52:55], v[52:55], v[4:7], v[96:99]
	s_nop 2
	v_exp_f32_e32 v164, v44
	v_exp_f32_e32 v165, v45
	v_exp_f32_e32 v168, v46
	s_waitcnt lgkmcnt(4)
	v_mfma_f32_16x16x32_bf16 v[56:59], v[56:59], v[8:11], v[96:99]
	v_exp_f32_e32 v169, v47
	v_exp_f32_e32 v162, v48
	v_exp_f32_e32 v163, v49
	s_waitcnt lgkmcnt(3)
	v_mfma_f32_16x16x32_bf16 v[60:63], v[60:63], v[4:7], v[104:107]
	v_exp_f32_e32 v166, v50
	v_exp_f32_e32 v167, v51
	v_exp_f32_e32 v172, v52
	s_waitcnt lgkmcnt(2)
	v_mfma_f32_16x16x32_bf16 v[44:47], v[64:67], v[8:11], v[104:107]
	v_exp_f32_e32 v170, v56
	v_exp_f32_e32 v173, v53
	v_exp_f32_e32 v176, v54
	s_waitcnt lgkmcnt(1)
	v_mfma_f32_16x16x32_bf16 v[48:51], v[68:71], v[4:7], v[80:83]
	v_exp_f32_e32 v177, v55
	v_exp_f32_e32 v174, v58
	v_exp_f32_e32 v175, v59
	s_waitcnt lgkmcnt(0)
	v_mfma_f32_16x16x32_bf16 v[64:67], v[72:75], v[8:11], v[80:83]
	v_exp_f32_e32 v171, v57
	v_exp_f32_e32 v180, v60
	v_exp_f32_e32 v178, v44
	v_exp_f32_e32 v181, v61
	v_exp_f32_e32 v179, v45
	v_exp_f32_e32 v184, v62
	v_exp_f32_e32 v185, v63
	v_exp_f32_e32 v182, v46
	v_exp_f32_e32 v183, v47
	v_exp_f32_e32 v188, v48
	v_exp_f32_e32 v186, v64
	v_exp_f32_e32 v189, v49
	v_exp_f32_e32 v192, v50
	v_exp_f32_e32 v193, v51
	v_exp_f32_e32 v190, v66
	v_exp_f32_e32 v191, v67
	v_exp_f32_e32 v187, v65
	v_pk_add_f32 v[52:53], v[168:169], v[176:177]
	v_pk_add_f32 v[54:55], v[164:165], v[172:173]
	v_pk_add_f32 v[56:57], v[166:167], v[174:175]
	v_pk_add_f32 v[58:59], v[162:163], v[170:171]
	v_pk_add_f32 v[44:45], v[54:55], v[180:181]
	v_pk_add_f32 v[46:47], v[52:53], v[184:185]
	v_pk_add_f32 v[52:53], v[58:59], v[178:179]
	v_pk_add_f32 v[54:55], v[56:57], v[182:183]
	v_pk_add_f32 v[46:47], v[46:47], v[192:193]
	v_pk_add_f32 v[44:45], v[44:45], v[188:189]
	v_pk_add_f32 v[48:49], v[54:55], v[190:191]
	v_pk_add_f32 v[50:51], v[52:53], v[186:187]
	v_mov_b32_e32 v53, v44
	v_mov_b32_e32 v52, v50
	v_mov_b32_e32 v44, v51
	v_mov_b32_e32 v50, v48
	v_mov_b32_e32 v51, v46
	v_mov_b32_e32 v46, v49
	v_pk_add_f32 v[44:45], v[52:53], v[44:45]
	v_pk_add_f32 v[46:47], v[50:51], v[46:47]
	s_nop 0
	v_pk_add_f32 v[194:195], v[44:45], v[46:47]
	s_nop 0
	v_add_f32_e32 v44, v195, v194
	v_cmp_ngt_f32_e32 vcc, s65, v44
	s_cbranch_vccz .LBB0_1395
	ds_read_b128 v[44:47], v213 offset:35840
	ds_read_b128 v[48:51], v213 offset:35904
	ds_read_b128 v[52:55], v213 offset:40192
	ds_read_b128 v[56:59], v213 offset:40256
	ds_read_b128 v[60:63], v213 offset:44544
	ds_read_b128 v[64:67], v213 offset:44608
	ds_read_b128 v[68:71], v213 offset:48896
	ds_read_b128 v[72:75], v213 offset:48960
	s_waitcnt lgkmcnt(7)
	v_mfma_f32_16x16x32_bf16 v[44:47], v[44:47], v[4:7], v[76:79]
	s_waitcnt lgkmcnt(6)
	v_mfma_f32_16x16x32_bf16 v[48:51], v[48:51], v[8:11], v[76:79]
	s_waitcnt lgkmcnt(5)
	v_mfma_f32_16x16x32_bf16 v[52:55], v[52:55], v[4:7], v[96:99]
	s_waitcnt lgkmcnt(4)
	v_mfma_f32_16x16x32_bf16 v[56:59], v[56:59], v[8:11], v[96:99]
	s_waitcnt lgkmcnt(3)
	v_mfma_f32_16x16x32_bf16 v[60:63], v[60:63], v[4:7], v[104:107]
	s_waitcnt lgkmcnt(2)
	v_mfma_f32_16x16x32_bf16 v[64:67], v[64:67], v[8:11], v[104:107]
	s_waitcnt lgkmcnt(1)
	v_mfma_f32_16x16x32_bf16 v[68:71], v[68:71], v[4:7], v[80:83]
	s_waitcnt lgkmcnt(0)
	v_mfma_f32_16x16x32_bf16 v[72:75], v[72:75], v[8:11], v[80:83]
	v_max3_f32 v84, v44, v48, s60
	v_max3_f32 v84, v84, v45, v49
	v_max3_f32 v84, v84, v46, v50
	v_max3_f32 v84, v84, v47, v51
	v_max3_f32 v84, v84, v52, v56
	v_max3_f32 v84, v84, v53, v57
	v_max3_f32 v84, v84, v54, v58
	v_max3_f32 v84, v84, v55, v59
	v_max3_f32 v84, v84, v60, v64
	v_max3_f32 v84, v84, v61, v65
	v_max3_f32 v84, v84, v62, v66
	v_max3_f32 v84, v84, v63, v67
	v_max3_f32 v84, v84, v68, v72
	v_max3_f32 v84, v84, v69, v73
	v_max3_f32 v84, v84, v70, v74
	v_max3_f32 v84, v84, v71, v75
	v_and_b32_e32 v86, 64, v198
	v_mov_b32_e32 v85, v84
	v_mov_b32_e32 v255, v84
	s_nop 1
	v_permlane16_swap_b32_e32 v85, v255
	s_waitcnt lgkmcnt(0)
	v_max_f32_e32 v84, v85, v255
	v_mov_b32_e32 v85, v84
	v_mov_b32_e32 v255, v84
	s_nop 1
	v_permlane32_swap_b32_e32 v85, v255
	s_waitcnt lgkmcnt(0)
; #define LAS __attribute__((address_space(3)))
; DI float fast_exp2(float x) { return __builtin_amdgcn_exp2f(x); }
; #define MFMA16(a, b, c) __builtin_amdgcn_mfma_f32_16x16x32_bf16((a), (b), (c), 0, 0, 0)
; DI u32x2 tr4(const LAS unsigned char* p) { return __builtin_bit_cast(u32x2, __builtin_amdgcn_ds_read_tr16_b64_v4i16((LAS v4i16_t*)p)); }
; DI bf16x8 packp(f32x4 a, f32x4 b) { return __builtin_bit_cast(bf16x8, pack8(a, b)); }
; DI void at_pv(AtState& S, const f32x4 (&s1)[4], const f32x4 (&s2)[4], float alpha, float ps1, float ps2, const LAS unsigned char* buf, int hh, int fq, int tq, int tp) {
;     S.l1 = S.l1 * alpha + ps1; S.l2 = S.l2 * alpha + ps2;
; #pragma unroll
;     for (int dt = 0; dt < 4; ++dt) { S.O1[dt] = S.O1[dt] * alpha; S.O2[dt] = S.O2[dt] * alpha; }
;     bf16x8 p1[2], p2[2];
; #pragma unroll
;     for (int s = 0; s < 2; ++s) { p1[s] = packp(s1[2 * s], s1[2 * s + 1]); p2[s] = packp(s2[2 * s], s2[2 * s + 1]); }
; #pragma unroll
;     for (int dh = 0; dh < 2; ++dh) {
;         bf16x8 vt[2][2];
; #pragma unroll
;         for (int d2 = 0; d2 < 2; ++d2)
; #pragma unroll
;             for (int s = 0; s < 2; ++s) { const int dt = 2 * dh + d2; const LAS unsigned char* vr = buf + AT_V + (32 * s + 4 * fq + tq) * 288 + (hh * 64 + 16 * dt + 4 * tp) * 2; vt[d2][s] = cat44(tr4(vr), tr4(vr + 16 * 288)); }
;         __builtin_amdgcn_s_setprio(1);
; #pragma unroll
;         for (int s = 0; s < 2; ++s)
; #pragma unroll
;             for (int d2 = 0; d2 < 2; ++d2) { const int dt = 2 * dh + d2; S.O1[dt] = MFMA16(vt[d2][s], p1[s], S.O1[dt]); S.O2[dt] = MFMA16(vt[d2][s], p2[s], S.O2[dt]); }
;         __builtin_amdgcn_s_setprio(0);
;         __builtin_amdgcn_sched_barrier(0);
;     }
; template <int VAR>
; DI void attn_tile(AtState& S, const LAS unsigned char* buf, const bf16x8 q1, const bf16x8 q2, int kt, bool diag, int qpos0, int qpos_l, float slope2, float adv, float decay, int hh, int fr, int fq) {
;     ...
;             const float bump = fmaxf(lm, 0.f);
;             const float alpha = decay * fast_exp2(-bump); S.ref += bump;
; #pragma unroll
;             for (int k4 = 0; k4 < 4; ++k4) { s1[k4] = s1[k4] - bump; s2[k4] = s2[k4] - bump; S.cinit[k4] = S.cinit[k4] - bump; }
;             at_exp(s1, s2, ps1, ps2);
;             at_pv(S, s1, s2, alpha, ps1, ps2, buf, hh, fq, tq, tp);
	v_max3_f32 v84, v255, v85, 0
	v_sub_f32_e32 v86, v47, v84
	v_sub_f32_e32 v87, v46, v84
	v_sub_f32_e32 v88, v45, v84
	v_sub_f32_e32 v89, v44, v84
	v_sub_f32_e32 v90, v51, v84
	v_sub_f32_e32 v91, v50, v84
	v_sub_f32_e32 v92, v49, v84
	v_sub_f32_e32 v93, v48, v84
	v_sub_f32_e32 v94, v55, v84
	v_sub_f32_e32 v95, v54, v84
	v_sub_f32_e32 v101, v53, v84
	v_sub_f32_e32 v102, v52, v84
	v_sub_f32_e32 v103, v59, v84
	v_sub_f32_e32 v151, v58, v84
	v_sub_f32_e32 v156, v57, v84
	v_sub_f32_e32 v157, v56, v84
	v_exp_f32_e32 v216, v89
	v_exp_f32_e32 v220, v93
	v_exp_f32_e32 v217, v88
	v_exp_f32_e32 v221, v92
	v_exp_f32_e32 v218, v87
	v_exp_f32_e32 v222, v91
	v_exp_f32_e32 v219, v86
	v_exp_f32_e32 v223, v90
	v_sub_f32_e32 v237, v63, v84
	v_sub_f32_e32 v236, v62, v84
	v_sub_f32_e32 v233, v61, v84
	v_sub_f32_e32 v232, v60, v84
	v_sub_f32_e32 v239, v67, v84
	v_sub_f32_e32 v238, v66, v84
	v_sub_f32_e32 v235, v65, v84
	v_sub_f32_e32 v234, v64, v84
	v_exp_f32_e32 v224, v102
	v_exp_f32_e32 v226, v157
	v_exp_f32_e32 v225, v101
	v_exp_f32_e32 v227, v156
	v_exp_f32_e32 v228, v95
	v_exp_f32_e32 v230, v151
	v_exp_f32_e32 v229, v94
	v_exp_f32_e32 v231, v103
	v_sub_f32_e32 v71, v71, v84
	v_sub_f32_e32 v70, v70, v84
	v_sub_f32_e32 v69, v69, v84
	v_sub_f32_e32 v68, v68, v84
	v_sub_f32_e32 v75, v75, v84
	v_sub_f32_e32 v74, v74, v84
	v_sub_f32_e32 v73, v73, v84
	v_sub_f32_e32 v72, v72, v84
	v_exp_f32_e32 v232, v232
	v_exp_f32_e32 v234, v234
	v_exp_f32_e32 v233, v233
	v_exp_f32_e32 v235, v235
	v_exp_f32_e32 v236, v236
	v_exp_f32_e32 v238, v238
	v_exp_f32_e32 v237, v237
	v_exp_f32_e32 v239, v239
	v_exp_f32_e32 v240, v68
	v_exp_f32_e32 v242, v72
	v_exp_f32_e32 v241, v69
	v_exp_f32_e32 v243, v73
	v_exp_f32_e32 v244, v70
	v_exp_f32_e32 v246, v74
	v_exp_f32_e32 v245, v71
	v_exp_f32_e32 v247, v75
	v_pk_add_f32 v[62:63], v[228:229], v[218:219]
	v_pk_add_f32 v[60:61], v[224:225], v[216:217]
	v_pk_add_f32 v[66:67], v[230:231], v[222:223]
	v_pk_add_f32 v[64:65], v[226:227], v[220:221]
	v_pk_add_f32 v[60:61], v[232:233], v[60:61]
	v_pk_add_f32 v[62:63], v[236:237], v[62:63]
	v_pk_add_f32 v[64:65], v[234:235], v[64:65]
	v_pk_add_f32 v[66:67], v[238:239], v[66:67]
	v_pk_add_f32 v[62:63], v[244:245], v[62:63]
	v_pk_add_f32 v[60:61], v[240:241], v[60:61]
	v_pk_add_f32 v[66:67], v[246:247], v[66:67]
	v_pk_add_f32 v[64:65], v[242:243], v[64:65]
	v_cvt_pk_bf16_f32 v216, v216, v217
	v_cvt_pk_bf16_f32 v217, v218, v219
	v_cvt_pk_bf16_f32 v218, v224, v225
	v_cvt_pk_bf16_f32 v219, v228, v229
	v_cvt_pk_bf16_f32 v220, v220, v221
	v_cvt_pk_bf16_f32 v221, v222, v223
	v_cvt_pk_bf16_f32 v222, v226, v227
	v_cvt_pk_bf16_f32 v223, v230, v231
	v_cvt_pk_bf16_f32 v224, v232, v233
	v_cvt_pk_bf16_f32 v225, v236, v237
	v_cvt_pk_bf16_f32 v226, v240, v241
	v_cvt_pk_bf16_f32 v227, v244, v245
	v_cvt_pk_bf16_f32 v228, v234, v235
	v_cvt_pk_bf16_f32 v229, v238, v239
	v_cvt_pk_bf16_f32 v230, v242, v243
	v_cvt_pk_bf16_f32 v231, v246, v247
	ds_read_b64_tr_b16 v[232:233], v208 offset:53248
	ds_read_b64_tr_b16 v[236:237], v208 offset:53280
	ds_read_b64_tr_b16 v[234:235], v208 offset:57856
	ds_read_b64_tr_b16 v[240:241], v208 offset:62464
	ds_read_b64_tr_b16 v[242:243], v209 offset:4608
	ds_read_b64_tr_b16 v[238:239], v208 offset:57888
	ds_read_b64_tr_b16 v[244:245], v208 offset:62496
	ds_read_b64_tr_b16 v[246:247], v210 offset:4608
	v_exp_f32_e64 v85, -v84
	v_mov_b32_e32 v68, v64
	v_mov_b32_e32 v69, v60
	v_mov_b32_e32 v60, v65
	v_mov_b32_e32 v64, v66
	v_mov_b32_e32 v65, v62
	v_mov_b32_e32 v62, v67
	v_pk_add_f32 v[60:61], v[68:69], v[60:61]
	v_pk_add_f32 v[62:63], v[64:65], v[62:63]
	v_mul_f32_e32 v100, v150, v85
	v_pk_add_f32 v[60:61], v[60:61], v[62:63]
	v_add_f32_e32 v214, v215, v84
	v_sub_f32_e32 v47, v79, v84
	v_sub_f32_e32 v46, v78, v84
	v_sub_f32_e32 v45, v77, v84
	v_sub_f32_e32 v44, v76, v84
	v_sub_f32_e32 v51, v99, v84
	v_sub_f32_e32 v50, v98, v84
	v_sub_f32_e32 v49, v97, v84
	v_sub_f32_e32 v48, v96, v84
	v_sub_f32_e32 v55, v107, v84
	v_sub_f32_e32 v54, v106, v84
	v_sub_f32_e32 v53, v105, v84
	v_sub_f32_e32 v52, v104, v84
	v_sub_f32_e32 v59, v83, v84
	v_sub_f32_e32 v58, v82, v84
	v_sub_f32_e32 v57, v81, v84
	v_sub_f32_e32 v56, v80, v84
	v_pk_fma_f32 v[156:157], v[158:159], v[100:101], v[60:61] op_sel_hi:[1,0,1]
	v_pk_mul_f32 v[62:63], v[122:123], v[100:101] op_sel_hi:[1,0]
	v_pk_mul_f32 v[60:61], v[120:121], v[100:101] op_sel_hi:[1,0]
	v_pk_mul_f32 v[66:67], v[118:119], v[100:101] op_sel_hi:[1,0]
	v_pk_mul_f32 v[64:65], v[116:117], v[100:101] op_sel_hi:[1,0]
	v_pk_mul_f32 v[70:71], v[114:115], v[100:101] op_sel_hi:[1,0]
	v_pk_mul_f32 v[68:69], v[112:113], v[100:101] op_sel_hi:[1,0]
	v_pk_mul_f32 v[74:75], v[110:111], v[100:101] op_sel_hi:[1,0]
	v_pk_mul_f32 v[72:73], v[108:109], v[100:101] op_sel_hi:[1,0]
	v_pk_mul_f32 v[86:87], v[138:139], v[100:101] op_sel_hi:[1,0]
	v_pk_mul_f32 v[84:85], v[136:137], v[100:101] op_sel_hi:[1,0]
	v_pk_mul_f32 v[90:91], v[134:135], v[100:101] op_sel_hi:[1,0]
	v_pk_mul_f32 v[88:89], v[132:133], v[100:101] op_sel_hi:[1,0]
	v_pk_mul_f32 v[94:95], v[130:131], v[100:101] op_sel_hi:[1,0]
	v_pk_mul_f32 v[92:93], v[128:129], v[100:101] op_sel_hi:[1,0]
	v_pk_mul_f32 v[102:103], v[126:127], v[100:101] op_sel_hi:[1,0]
	v_pk_mul_f32 v[100:101], v[124:125], v[100:101] op_sel_hi:[1,0]
	s_waitcnt lgkmcnt(5)
	v_mfma_f32_16x16x32_bf16 v[60:63], v[232:235], v[216:219], v[60:63]
	v_mfma_f32_16x16x32_bf16 v[232:235], v[232:235], v[220:223], v[64:67]
	s_waitcnt lgkmcnt(2)
	v_mfma_f32_16x16x32_bf16 v[68:71], v[236:239], v[216:219], v[68:71]
	v_mfma_f32_16x16x32_bf16 v[236:239], v[236:239], v[220:223], v[72:75]
	v_mfma_f32_16x16x32_bf16 v[64:67], v[240:243], v[224:227], v[60:63]
	v_mfma_f32_16x16x32_bf16 v[72:75], v[240:243], v[228:231], v[232:235]
	s_waitcnt lgkmcnt(0)
	v_mfma_f32_16x16x32_bf16 v[60:63], v[244:247], v[224:227], v[68:71]
	v_mfma_f32_16x16x32_bf16 v[68:71], v[244:247], v[228:231], v[236:239]
	ds_read_b64_tr_b16 v[232:233], v208 offset:53312
	s_nop 0
	ds_read_b64_tr_b16 v[236:237], v208 offset:53344
	ds_read_b64_tr_b16 v[234:235], v208 offset:57920
	ds_read_b64_tr_b16 v[238:239], v208 offset:57952
	ds_read_b64_tr_b16 v[240:241], v208 offset:62528
	ds_read_b64_tr_b16 v[242:243], v211 offset:4608
	ds_read_b64_tr_b16 v[246:247], v212 offset:4608
	ds_read_b64_tr_b16 v[244:245], v208 offset:62560
	s_waitcnt lgkmcnt(5)
	v_mfma_f32_16x16x32_bf16 v[84:87], v[232:235], v[216:219], v[84:87]
	v_mfma_f32_16x16x32_bf16 v[232:235], v[232:235], v[220:223], v[88:91]
	s_waitcnt lgkmcnt(4)
	v_mfma_f32_16x16x32_bf16 v[92:95], v[236:239], v[216:219], v[92:95]
	v_mfma_f32_16x16x32_bf16 v[216:219], v[236:239], v[220:223], v[100:103]
	s_waitcnt lgkmcnt(2)
	v_mfma_f32_16x16x32_bf16 v[88:91], v[240:243], v[224:227], v[84:87]
	v_mfma_f32_16x16x32_bf16 v[100:103], v[240:243], v[228:231], v[232:235]
	s_waitcnt lgkmcnt(0)
	v_mfma_f32_16x16x32_bf16 v[84:87], v[244:247], v[224:227], v[92:95]
	v_mfma_f32_16x16x32_bf16 v[92:95], v[244:247], v[228:231], v[216:219]
	s_cbranch_execnz .LBB0_1390
; #define LAS __attribute__((address_space(3)))
; #define MFMA16(a, b, c) __builtin_amdgcn_mfma_f32_16x16x32_bf16((a), (b), (c), 0, 0, 0)
; DI u32x2 tr4(const LAS unsigned char* p) { return __builtin_bit_cast(u32x2, __builtin_amdgcn_ds_read_tr16_b64_v4i16((LAS v4i16_t*)p)); }
; DI bf16x8 packp(f32x4 a, f32x4 b) { return __builtin_bit_cast(bf16x8, pack8(a, b)); }
; DI void at_pv(AtState& S, const f32x4 (&s1)[4], const f32x4 (&s2)[4], float alpha, float ps1, float ps2, const LAS unsigned char* buf, int hh, int fq, int tq, int tp) {
;     S.l1 = S.l1 * alpha + ps1; S.l2 = S.l2 * alpha + ps2;
; #pragma unroll
;     for (int dt = 0; dt < 4; ++dt) { S.O1[dt] = S.O1[dt] * alpha; S.O2[dt] = S.O2[dt] * alpha; }
;     bf16x8 p1[2], p2[2];
; #pragma unroll
;     for (int s = 0; s < 2; ++s) { p1[s] = packp(s1[2 * s], s1[2 * s + 1]); p2[s] = packp(s2[2 * s], s2[2 * s + 1]); }
; #pragma unroll
;     for (int dh = 0; dh < 2; ++dh) {
;         bf16x8 vt[2][2];
; #pragma unroll
;         for (int d2 = 0; d2 < 2; ++d2)
; #pragma unroll
;             for (int s = 0; s < 2; ++s) { const int dt = 2 * dh + d2; const LAS unsigned char* vr = buf + AT_V + (32 * s + 4 * fq + tq) * 288 + (hh * 64 + 16 * dt + 4 * tp) * 2; vt[d2][s] = cat44(tr4(vr), tr4(vr + 16 * 288)); }
;         __builtin_amdgcn_s_setprio(1);
; #pragma unroll
;         for (int s = 0; s < 2; ++s)
; #pragma unroll
;             for (int d2 = 0; d2 < 2; ++d2) { const int dt = 2 * dh + d2; S.O1[dt] = MFMA16(vt[d2][s], p1[s], S.O1[dt]); S.O2[dt] = MFMA16(vt[d2][s], p2[s], S.O2[dt]); }
;         __builtin_amdgcn_s_setprio(0);
;         __builtin_amdgcn_sched_barrier(0);
;     }
; template <int VAR>
; DI void attn_tile(AtState& S, const LAS unsigned char* buf, const bf16x8 q1, const bf16x8 q2, int kt, bool diag, int qpos0, int qpos_l, float slope2, float adv, float decay, int hh, int fr, int fq) {
;     ...
;         } else {
;             asm volatile("; attention: fast tail" ::: "memory");
;             at_pv(S, s1, s2, decay, ps1, ps2, buf, hh, fq, tq, tp);
.LBB0_1389:
	s_nop 0
	v_cvt_pk_bf16_f32 v216, v164, v165
	v_cvt_pk_bf16_f32 v219, v176, v177
	v_cvt_pk_bf16_f32 v165, v174, v175
	ds_read_b64_tr_b16 v[60:61], v208 offset:53248
	ds_read_b64_tr_b16 v[64:65], v208 offset:53280
	ds_read_b64_tr_b16 v[62:63], v208 offset:57856
	ds_read_b64_tr_b16 v[68:69], v208 offset:62464
	ds_read_b64_tr_b16 v[70:71], v209 offset:4608
	ds_read_b64_tr_b16 v[66:67], v208 offset:57888
	ds_read_b64_tr_b16 v[174:175], v208 offset:62496
	ds_read_b64_tr_b16 v[176:177], v210 offset:4608
	v_mov_b32_e32 v151, v150
	v_pk_fma_f32 v[156:157], v[154:155], v[158:159], v[194:195]
	v_pk_mul_f32 v[46:47], v[150:151], v[122:123]
	v_pk_mul_f32 v[44:45], v[152:153], v[120:121]
	v_pk_mul_f32 v[50:51], v[150:151], v[118:119]
	v_pk_mul_f32 v[48:49], v[152:153], v[116:117]
	v_pk_mul_f32 v[54:55], v[150:151], v[114:115]
	v_pk_mul_f32 v[52:53], v[152:153], v[112:113]
	v_pk_mul_f32 v[58:59], v[150:151], v[110:111]
	v_pk_mul_f32 v[56:57], v[152:153], v[108:109]
	v_pk_mul_f32 v[86:87], v[150:151], v[138:139]
	v_pk_mul_f32 v[84:85], v[152:153], v[136:137]
	v_pk_mul_f32 v[90:91], v[150:151], v[134:135]
	v_pk_mul_f32 v[88:89], v[152:153], v[132:133]
	v_pk_mul_f32 v[94:95], v[150:151], v[130:131]
	v_pk_mul_f32 v[92:93], v[152:153], v[128:129]
	v_pk_mul_f32 v[102:103], v[150:151], v[126:127]
	v_pk_mul_f32 v[100:101], v[152:153], v[124:125]
	v_cvt_pk_bf16_f32 v217, v168, v169
	v_cvt_pk_bf16_f32 v218, v172, v173
	v_cvt_pk_bf16_f32 v162, v162, v163
	v_cvt_pk_bf16_f32 v163, v166, v167
	v_cvt_pk_bf16_f32 v164, v170, v171
	v_cvt_pk_bf16_f32 v166, v180, v181
	v_cvt_pk_bf16_f32 v167, v184, v185
	v_cvt_pk_bf16_f32 v168, v188, v189
	v_cvt_pk_bf16_f32 v169, v192, v193
	v_cvt_pk_bf16_f32 v170, v178, v179
	v_cvt_pk_bf16_f32 v171, v182, v183
	v_cvt_pk_bf16_f32 v172, v186, v187
	v_cvt_pk_bf16_f32 v173, v190, v191
	s_waitcnt lgkmcnt(5)
	v_mfma_f32_16x16x32_bf16 v[44:47], v[60:63], v[216:219], v[44:47]
	v_mfma_f32_16x16x32_bf16 v[48:51], v[60:63], v[162:165], v[48:51]
	s_waitcnt lgkmcnt(2)
	v_mfma_f32_16x16x32_bf16 v[52:55], v[64:67], v[216:219], v[52:55]
	v_mfma_f32_16x16x32_bf16 v[56:59], v[64:67], v[162:165], v[56:59]
	v_mfma_f32_16x16x32_bf16 v[64:67], v[68:71], v[166:169], v[44:47]
	v_mfma_f32_16x16x32_bf16 v[72:75], v[68:71], v[170:173], v[48:51]
	s_waitcnt lgkmcnt(0)
	v_mfma_f32_16x16x32_bf16 v[60:63], v[174:177], v[166:169], v[52:55]
	v_mfma_f32_16x16x32_bf16 v[68:71], v[174:177], v[170:173], v[56:59]
	s_waitcnt vmcnt(4)
	ds_write_b128 v143, v[28:31]
	ds_write_b128 v202, v[32:35] offset:17408
	ds_write_b128 v203, v[36:39]
	ds_write_b128 v204, v[40:43] offset:17408
	ds_read_b64_tr_b16 v[44:45], v208 offset:53312
	ds_read_b64_tr_b16 v[48:49], v208 offset:53344
	ds_read_b64_tr_b16 v[46:47], v208 offset:57920
	ds_read_b64_tr_b16 v[50:51], v208 offset:57952
	ds_read_b64_tr_b16 v[52:53], v208 offset:62528
	ds_read_b64_tr_b16 v[54:55], v211 offset:4608
	ds_read_b64_tr_b16 v[58:59], v212 offset:4608
	ds_read_b64_tr_b16 v[56:57], v208 offset:62560
	s_waitcnt lgkmcnt(5)
	v_mfma_f32_16x16x32_bf16 v[84:87], v[44:47], v[216:219], v[84:87]
	v_mfma_f32_16x16x32_bf16 v[44:47], v[44:47], v[162:165], v[88:91]
	s_waitcnt lgkmcnt(4)
	v_mfma_f32_16x16x32_bf16 v[92:95], v[48:51], v[216:219], v[92:95]
	v_mfma_f32_16x16x32_bf16 v[48:51], v[48:51], v[162:165], v[100:103]
	s_waitcnt lgkmcnt(2)
	v_mfma_f32_16x16x32_bf16 v[88:91], v[52:55], v[166:169], v[84:87]
	v_mfma_f32_16x16x32_bf16 v[100:103], v[52:55], v[170:173], v[44:47]
	s_waitcnt lgkmcnt(0)
	v_mfma_f32_16x16x32_bf16 v[84:87], v[56:59], v[166:169], v[92:95]
	v_mfma_f32_16x16x32_bf16 v[92:95], v[56:59], v[170:173], v[48:51]
	v_mov_b64_e32 v[56:57], v[80:81]
	v_mov_b64_e32 v[44:45], v[76:77]
	v_mov_b64_e32 v[48:49], v[96:97]
	v_mov_b64_e32 v[52:53], v[104:105]
	v_mov_b32_e32 v214, v215
	v_mov_b64_e32 v[58:59], v[82:83]
	v_mov_b64_e32 v[46:47], v[78:79]
	v_mov_b64_e32 v[50:51], v[98:99]
	v_mov_b64_e32 v[54:55], v[106:107]
	s_mov_b64 s[14:15], 0
	s_branch .Lcommit_done_B

; #define LAS __attribute__((address_space(3)))
; #define MFMA16(a, b, c) __builtin_amdgcn_mfma_f32_16x16x32_bf16((a), (b), (c), 0, 0, 0)
; DI void at_qk(f32x4 (&s1)[4], f32x4 (&s2)[4], const LAS unsigned char* buf, const bf16x8 q1, const bf16x8 q2, const f32x4 (&ci)[4], int hh, int fr, int fq) {
; #pragma unroll
;     for (int k4 = 0; k4 < 4; ++k4) { const LAS unsigned char* kr = buf + AT_K + (16 * k4 + fr) * 272 + hh * 128 + fq * 16;
;         s1[k4] = MFMA16(ld8l(kr), q1, ci[k4]); s2[k4] = MFMA16(ld8l(kr + 64), q2, ci[k4]); }
; }
; template <int VAR>
; DI void attn_tile(AtState& S, const LAS unsigned char* buf, const bf16x8 q1, const bf16x8 q2, int kt, bool diag, int qpos0, int qpos_l, float slope2, float adv, float decay, int hh, int fr, int fq) {
;     ...
;         asm volatile("; attention: exact tile" ::: "memory");
;         { f32x4 z[4];
; #pragma unroll
;           for (int k4 = 0; k4 < 4; ++k4) z[k4] = (f32x4){0.f, 0.f, 0.f, 0.f};
;           at_qk(s1, s2, buf, q1, q2, z, hh, fr, fq); }
;         int ql = qpos_l - 4 * fq; asm volatile("" : "+v"(ql));
;         const float dk = slope2 * (float)(qpos0 - kt * 64);
;         float mx = -1e30f;
; #pragma unroll
;         for (int k4 = 0; k4 < 4; ++k4)
; #pragma unroll
;             for (int j = 0; j < 4; ++j) { const float g = slope2 * (float)(16 * k4 + j - ql); const float bias = diag ? -fabsf(g) : g - dk;
;                 s1[k4][j] += bias; s2[k4][j] += bias; mx = fmaxf(mx, fmaxf(s1[k4][j], s2[k4][j])); }
;         mx = fmaxf(mx, __shfl_xor(mx, 16)); mx = fmaxf(mx, __shfl_xor(mx, 32));
.LBB0_1391:
	s_andn2_b64 vcc, exec, s[14:15]
	s_cbranch_vccnz .LBB0_1393
	ds_read_b128 v[44:47], v213 offset:35840
	ds_read_b128 v[48:51], v213 offset:35904
	v_mov_b32_e32 v86, v206
	ds_read_b128 v[52:55], v213 offset:40192
	ds_read_b128 v[56:59], v213 offset:40256
	ds_read_b128 v[60:63], v213 offset:44544
	ds_read_b128 v[64:67], v213 offset:44608
	ds_read_b128 v[68:71], v213 offset:48896
	ds_read_b128 v[72:75], v213 offset:48960
	s_waitcnt lgkmcnt(7)
	v_mfma_f32_16x16x32_bf16 v[44:47], v[44:47], v[4:7], 0
	v_sub_u32_e32 v84, 0, v86
	v_sub_u32_e32 v85, 1, v86
	v_cvt_f32_i32_e32 v85, v85
	v_cvt_f32_i32_e32 v84, v84
	s_waitcnt lgkmcnt(6)
	v_mfma_f32_16x16x32_bf16 v[48:51], v[48:51], v[8:11], 0
	v_mul_f32_e64 v84, v148, v84
	v_mul_f32_e64 v85, v149, v85
	v_and_b32_e32 v85, 0x7fffffff, v85
	v_and_b32_e32 v84, 0x7fffffff, v84
	s_nop 3
	v_pk_add_f32 v[48:49], v[48:49], v[84:85] neg_lo:[0,1] neg_hi:[0,1]
	v_pk_add_f32 v[44:45], v[44:45], v[84:85] neg_lo:[0,1] neg_hi:[0,1]
	v_sub_u32_e32 v84, 2, v86
	v_sub_u32_e32 v85, 3, v86
	v_cvt_f32_i32_e32 v85, v85
	v_cvt_f32_i32_e32 v84, v84
	s_waitcnt lgkmcnt(5)
	v_mfma_f32_16x16x32_bf16 v[52:55], v[52:55], v[4:7], 0
	v_max_f32_e32 v87, v44, v48
	v_max_f32_e32 v88, v45, v49
	v_pk_mul_f32 v[84:85], v[148:149], v[84:85]
	s_waitcnt lgkmcnt(4)
	v_mfma_f32_16x16x32_bf16 v[56:59], v[56:59], v[8:11], 0
	v_and_b32_e32 v85, 0x7fffffff, v85
	v_and_b32_e32 v84, 0x7fffffff, v84
	v_pk_add_f32 v[50:51], v[50:51], v[84:85] neg_lo:[0,1] neg_hi:[0,1]
	v_pk_add_f32 v[46:47], v[46:47], v[84:85] neg_lo:[0,1] neg_hi:[0,1]
	v_sub_u32_e32 v84, 16, v86
	v_sub_u32_e32 v85, 17, v86
	v_cvt_f32_i32_e32 v85, v85
	v_cvt_f32_i32_e32 v84, v84
	s_waitcnt lgkmcnt(3)
	v_mfma_f32_16x16x32_bf16 v[60:63], v[60:63], v[4:7], 0
	v_max3_f32 v87, v87, s60, v88
	v_max_f32_e32 v88, v46, v50
	v_pk_mul_f32 v[84:85], v[148:149], v[84:85]
	s_waitcnt lgkmcnt(2)
	v_mfma_f32_16x16x32_bf16 v[64:67], v[64:67], v[8:11], 0
	v_and_b32_e32 v85, 0x7fffffff, v85
	v_and_b32_e32 v84, 0x7fffffff, v84
	v_pk_add_f32 v[56:57], v[56:57], v[84:85] neg_lo:[0,1] neg_hi:[0,1]
	v_pk_add_f32 v[52:53], v[52:53], v[84:85] neg_lo:[0,1] neg_hi:[0,1]
	v_sub_u32_e32 v84, 18, v86
	v_sub_u32_e32 v85, 19, v86
	v_cvt_f32_i32_e32 v85, v85
	v_cvt_f32_i32_e32 v84, v84
	s_waitcnt lgkmcnt(1)
	v_mfma_f32_16x16x32_bf16 v[68:71], v[68:71], v[4:7], 0
	v_max_f32_e32 v89, v47, v51
	v_max3_f32 v87, v87, v88, v89
	v_pk_mul_f32 v[84:85], v[148:149], v[84:85]
	s_waitcnt lgkmcnt(0)
	v_mfma_f32_16x16x32_bf16 v[72:75], v[72:75], v[8:11], 0
	v_and_b32_e32 v85, 0x7fffffff, v85
	v_and_b32_e32 v84, 0x7fffffff, v84
	v_pk_add_f32 v[58:59], v[58:59], v[84:85] neg_lo:[0,1] neg_hi:[0,1]
	v_pk_add_f32 v[54:55], v[54:55], v[84:85] neg_lo:[0,1] neg_hi:[0,1]
	v_sub_u32_e32 v84, 32, v86
	v_sub_u32_e32 v85, 33, v86
	v_cvt_f32_i32_e32 v85, v85
	v_cvt_f32_i32_e32 v84, v84
	v_max_f32_e32 v88, v52, v56
	v_max_f32_e32 v89, v53, v57
	v_max3_f32 v87, v87, v88, v89
	v_pk_mul_f32 v[84:85], v[148:149], v[84:85]
	v_max_f32_e32 v88, v54, v58
	v_and_b32_e32 v85, 0x7fffffff, v85
	v_and_b32_e32 v84, 0x7fffffff, v84
	v_pk_add_f32 v[64:65], v[64:65], v[84:85] neg_lo:[0,1] neg_hi:[0,1]
	v_pk_add_f32 v[60:61], v[60:61], v[84:85] neg_lo:[0,1] neg_hi:[0,1]
	v_sub_u32_e32 v84, 34, v86
	v_sub_u32_e32 v85, 35, v86
	v_cvt_f32_i32_e32 v85, v85
	v_cvt_f32_i32_e32 v84, v84
	v_max_f32_e32 v89, v55, v59
	v_max3_f32 v87, v87, v88, v89
	v_max_f32_e32 v88, v60, v64
	v_pk_mul_f32 v[84:85], v[148:149], v[84:85]
	v_max_f32_e32 v89, v61, v65
	v_and_b32_e32 v85, 0x7fffffff, v85
	v_and_b32_e32 v84, 0x7fffffff, v84
	v_pk_add_f32 v[66:67], v[66:67], v[84:85] neg_lo:[0,1] neg_hi:[0,1]
	v_pk_add_f32 v[62:63], v[62:63], v[84:85] neg_lo:[0,1] neg_hi:[0,1]
	v_sub_u32_e32 v84, 48, v86
	v_sub_u32_e32 v85, 49, v86
	v_cvt_f32_i32_e32 v85, v85
	v_cvt_f32_i32_e32 v84, v84
	v_max3_f32 v87, v87, v88, v89
	v_max_f32_e32 v88, v62, v66
	v_max_f32_e32 v89, v63, v67
	v_pk_mul_f32 v[84:85], v[148:149], v[84:85]
	v_max3_f32 v87, v87, v88, v89
	v_and_b32_e32 v85, 0x7fffffff, v85
	v_and_b32_e32 v84, 0x7fffffff, v84
	v_pk_add_f32 v[72:73], v[72:73], v[84:85] neg_lo:[0,1] neg_hi:[0,1]
	v_pk_add_f32 v[68:69], v[68:69], v[84:85] neg_lo:[0,1] neg_hi:[0,1]
	v_sub_u32_e32 v84, 50, v86
	v_sub_u32_e32 v85, 51, v86
	v_cvt_f32_i32_e32 v85, v85
	v_cvt_f32_i32_e32 v84, v84
	v_max_f32_e32 v86, v68, v72
	v_max_f32_e32 v88, v69, v73
	v_max3_f32 v86, v87, v86, v88
	v_pk_mul_f32 v[84:85], v[148:149], v[84:85]
	s_nop 0
	v_and_b32_e32 v85, 0x7fffffff, v85
	v_and_b32_e32 v84, 0x7fffffff, v84
	v_pk_add_f32 v[74:75], v[74:75], v[84:85] neg_lo:[0,1] neg_hi:[0,1]
	v_pk_add_f32 v[70:71], v[70:71], v[84:85] neg_lo:[0,1] neg_hi:[0,1]
	s_nop 0
	v_max_f32_e32 v84, v70, v74
	v_max_f32_e32 v85, v71, v75
	v_max3_f32 v84, v86, v84, v85
	v_and_b32_e32 v86, 64, v198
	v_mov_b32_e32 v85, v84
	v_mov_b32_e32 v255, v84
	s_nop 1
	v_permlane16_swap_b32_e32 v85, v255
	s_waitcnt lgkmcnt(0)
	v_max_f32_e32 v84, v85, v255
	v_mov_b32_e32 v85, v84
	v_mov_b32_e32 v255, v84
	s_nop 1
	v_permlane32_swap_b32_e32 v85, v255
	s_waitcnt lgkmcnt(0)
; #define LAS __attribute__((address_space(3)))
; DI float fast_exp2(float x) { return __builtin_amdgcn_exp2f(x); }
; #define MFMA16(a, b, c) __builtin_amdgcn_mfma_f32_16x16x32_bf16((a), (b), (c), 0, 0, 0)
; DI bf16x8 packp(f32x4 a, f32x4 b) { return __builtin_bit_cast(bf16x8, pack8(a, b)); }
; DI void at_pv(AtState& S, const f32x4 (&s1)[4], const f32x4 (&s2)[4], float alpha, float ps1, float ps2, const LAS unsigned char* buf, int hh, int fq, int tq, int tp) {
;     S.l1 = S.l1 * alpha + ps1; S.l2 = S.l2 * alpha + ps2;
; #pragma unroll
;     for (int dt = 0; dt < 4; ++dt) { S.O1[dt] = S.O1[dt] * alpha; S.O2[dt] = S.O2[dt] * alpha; }
;     bf16x8 p1[2], p2[2];
; #pragma unroll
;     for (int s = 0; s < 2; ++s) { p1[s] = packp(s1[2 * s], s1[2 * s + 1]); p2[s] = packp(s2[2 * s], s2[2 * s + 1]); }
; #pragma unroll
;     for (int dh = 0; dh < 2; ++dh) {
;         bf16x8 vt[2][2];
; #pragma unroll
;         for (int d2 = 0; d2 < 2; ++d2)
; #pragma unroll
;             for (int s = 0; s < 2; ++s) { const int dt = 2 * dh + d2; const LAS unsigned char* vr = buf + AT_V + (32 * s + 4 * fq + tq) * 288 + (hh * 64 + 16 * dt + 4 * tp) * 2; vt[d2][s] = cat44(tr4(vr), tr4(vr + 16 * 288)); }
;         __builtin_amdgcn_s_setprio(1);
; #pragma unroll
;         for (int s = 0; s < 2; ++s)
; #pragma unroll
;             for (int d2 = 0; d2 < 2; ++d2) { const int dt = 2 * dh + d2; S.O1[dt] = MFMA16(vt[d2][s], p1[s], S.O1[dt]); S.O2[dt] = MFMA16(vt[d2][s], p2[s], S.O2[dt]); }
;         __builtin_amdgcn_s_setprio(0);
;         __builtin_amdgcn_sched_barrier(0);
;     }
; template <int VAR>
; DI void attn_tile(AtState& S, const LAS unsigned char* buf, const bf16x8 q1, const bf16x8 q2, int kt, bool diag, int qpos0, int qpos_l, float slope2, float adv, float decay, int hh, int fr, int fq) {
;     ...
;         const float nref = fmaxf(S.ref, mx);
;         const float alpha = fast_exp2(S.ref - nref); S.ref = nref;
; #pragma unroll
;         for (int k4 = 0; k4 < 4; ++k4) { s1[k4] = s1[k4] - nref; s2[k4] = s2[k4] - nref; }
;         if (kt == 0) { const float c0 = -slope2 * (float)qpos0 - S.ref;
; #pragma unroll
;             for (int k4 = 0; k4 < 4; ++k4)
; #pragma unroll
;                 for (int j = 0; j < 4; ++j) S.cinit[k4][j] = slope2 * (float)(16 * k4 + j - ql) + c0; }
;         at_exp(s1, s2, ps1, ps2);
;         at_pv(S, s1, s2, alpha, ps1, ps2, buf, hh, fq, tq, tp);
	v_max3_f32 v214, v3, v255, v85
	v_sub_f32_e32 v47, v47, v214
	v_sub_f32_e32 v46, v46, v214
	v_sub_f32_e32 v45, v45, v214
	v_sub_f32_e32 v44, v44, v214
	v_sub_f32_e32 v51, v51, v214
	v_sub_f32_e32 v50, v50, v214
	v_sub_f32_e32 v49, v49, v214
	v_sub_f32_e32 v48, v48, v214
	v_sub_f32_e32 v55, v55, v214
	v_sub_f32_e32 v54, v54, v214
	v_sub_f32_e32 v53, v53, v214
	v_sub_f32_e32 v52, v52, v214
	v_sub_f32_e32 v59, v59, v214
	v_sub_f32_e32 v58, v58, v214
	v_sub_f32_e32 v57, v57, v214
	v_sub_f32_e32 v56, v56, v214
	v_sub_f32_e32 v84, v63, v214
	v_sub_f32_e32 v85, v62, v214
	v_sub_f32_e32 v87, v67, v214
	v_sub_f32_e32 v88, v66, v214
	v_sub_f32_e32 v89, v65, v214
	v_sub_f32_e32 v90, v64, v214
	v_sub_f32_e32 v93, v69, v214
	v_sub_f32_e32 v94, v68, v214
	v_exp_f32_e32 v62, v44
	v_exp_f32_e32 v64, v48
	v_exp_f32_e32 v63, v45
	v_exp_f32_e32 v65, v49
	v_exp_f32_e32 v66, v46
	v_exp_f32_e32 v67, v47
	v_exp_f32_e32 v68, v50
	v_exp_f32_e32 v69, v51
	v_sub_f32_e32 v61, v61, v214
	v_sub_f32_e32 v86, v60, v214
	v_sub_f32_e32 v91, v71, v214
	v_sub_f32_e32 v92, v70, v214
	v_sub_f32_e32 v95, v75, v214
	v_sub_f32_e32 v100, v74, v214
	v_sub_f32_e32 v101, v73, v214
	v_sub_f32_e32 v102, v72, v214
	v_exp_f32_e32 v70, v52
	v_exp_f32_e32 v72, v56
	v_exp_f32_e32 v71, v53
	v_exp_f32_e32 v74, v54
	v_exp_f32_e32 v75, v55
	v_exp_f32_e32 v162, v58
	v_exp_f32_e32 v163, v59
	v_exp_f32_e32 v73, v57
	v_exp_f32_e32 v164, v86
	v_exp_f32_e32 v166, v90
	v_exp_f32_e32 v165, v61
	v_exp_f32_e32 v167, v89
	v_exp_f32_e32 v168, v85
	v_exp_f32_e32 v169, v84
	v_exp_f32_e32 v170, v88
	v_exp_f32_e32 v171, v87
	v_exp_f32_e32 v172, v94
	v_exp_f32_e32 v174, v102
	v_exp_f32_e32 v173, v93
	v_exp_f32_e32 v176, v92
	v_exp_f32_e32 v177, v91
	v_exp_f32_e32 v178, v100
	v_exp_f32_e32 v179, v95
	v_exp_f32_e32 v175, v101
	v_pk_add_f32 v[46:47], v[74:75], v[66:67]
	v_pk_add_f32 v[44:45], v[70:71], v[62:63]
	v_pk_add_f32 v[50:51], v[162:163], v[68:69]
	v_pk_add_f32 v[48:49], v[72:73], v[64:65]
	v_sub_f32_e32 v3, v3, v214
	v_pk_add_f32 v[44:45], v[164:165], v[44:45]
	v_pk_add_f32 v[46:47], v[168:169], v[46:47]
	v_pk_add_f32 v[48:49], v[166:167], v[48:49]
	v_pk_add_f32 v[50:51], v[170:171], v[50:51]
	v_exp_f32_e32 v60, v3
	v_pk_add_f32 v[46:47], v[176:177], v[46:47]
	v_pk_add_f32 v[44:45], v[172:173], v[44:45]
	v_pk_add_f32 v[50:51], v[178:179], v[50:51]
	v_pk_add_f32 v[48:49], v[174:175], v[48:49]
	v_mov_b32_e32 v53, v44
	v_mov_b32_e32 v52, v48
	v_mov_b32_e32 v44, v49
	v_mov_b32_e32 v48, v50
	v_mov_b32_e32 v49, v46
	v_mov_b32_e32 v46, v51
	v_pk_add_f32 v[44:45], v[52:53], v[44:45]
	v_pk_add_f32 v[46:47], v[48:49], v[46:47]
	v_pk_mul_f32 v[50:51], v[118:119], v[60:61] op_sel_hi:[1,0]
	v_pk_add_f32 v[44:45], v[44:45], v[46:47]
	v_pk_mul_f32 v[46:47], v[122:123], v[60:61] op_sel_hi:[1,0]
	v_pk_fma_f32 v[156:157], v[158:159], v[60:61], v[44:45] op_sel_hi:[1,0,1]
	v_pk_mul_f32 v[44:45], v[120:121], v[60:61] op_sel_hi:[1,0]
	v_pk_mul_f32 v[48:49], v[116:117], v[60:61] op_sel_hi:[1,0]
	v_pk_mul_f32 v[54:55], v[114:115], v[60:61] op_sel_hi:[1,0]
	v_pk_mul_f32 v[52:53], v[112:113], v[60:61] op_sel_hi:[1,0]
	v_pk_mul_f32 v[58:59], v[110:111], v[60:61] op_sel_hi:[1,0]
	v_pk_mul_f32 v[56:57], v[108:109], v[60:61] op_sel_hi:[1,0]
	v_pk_mul_f32 v[86:87], v[138:139], v[60:61] op_sel_hi:[1,0]
	v_pk_mul_f32 v[84:85], v[136:137], v[60:61] op_sel_hi:[1,0]
	v_pk_mul_f32 v[90:91], v[134:135], v[60:61] op_sel_hi:[1,0]
	v_pk_mul_f32 v[88:89], v[132:133], v[60:61] op_sel_hi:[1,0]
	v_pk_mul_f32 v[94:95], v[130:131], v[60:61] op_sel_hi:[1,0]
	v_pk_mul_f32 v[92:93], v[128:129], v[60:61] op_sel_hi:[1,0]
	v_pk_mul_f32 v[102:103], v[126:127], v[60:61] op_sel_hi:[1,0]
	v_pk_mul_f32 v[100:101], v[124:125], v[60:61] op_sel_hi:[1,0]
	v_cvt_pk_bf16_f32 v108, v62, v63
	v_cvt_pk_bf16_f32 v109, v66, v67
	v_cvt_pk_bf16_f32 v110, v70, v71
	v_cvt_pk_bf16_f32 v112, v64, v65
	v_cvt_pk_bf16_f32 v113, v68, v69
	ds_read_b64_tr_b16 v[60:61], v208 offset:53248
	ds_read_b64_tr_b16 v[64:65], v208 offset:53280
	ds_read_b64_tr_b16 v[62:63], v208 offset:57856
	ds_read_b64_tr_b16 v[66:67], v208 offset:57888
	ds_read_b64_tr_b16 v[68:69], v208 offset:62464
	ds_read_b64_tr_b16 v[70:71], v209 offset:4608
	ds_read_b64_tr_b16 v[122:123], v210 offset:4608
	ds_read_b64_tr_b16 v[120:121], v208 offset:62496
	v_cvt_pk_bf16_f32 v111, v74, v75
	v_cvt_pk_bf16_f32 v114, v72, v73
	v_cvt_pk_bf16_f32 v115, v162, v163
	v_cvt_pk_bf16_f32 v116, v164, v165
	v_cvt_pk_bf16_f32 v117, v168, v169
	v_cvt_pk_bf16_f32 v118, v172, v173
	v_cvt_pk_bf16_f32 v119, v176, v177
	v_cvt_pk_bf16_f32 v124, v166, v167
	v_cvt_pk_bf16_f32 v125, v170, v171
	v_cvt_pk_bf16_f32 v126, v174, v175
	v_cvt_pk_bf16_f32 v127, v178, v179
	s_waitcnt lgkmcnt(5)
	v_mfma_f32_16x16x32_bf16 v[44:47], v[60:63], v[108:111], v[44:47]
	v_mfma_f32_16x16x32_bf16 v[48:51], v[60:63], v[112:115], v[48:51]
	s_waitcnt lgkmcnt(4)
	v_mfma_f32_16x16x32_bf16 v[52:55], v[64:67], v[108:111], v[52:55]
	v_mfma_f32_16x16x32_bf16 v[56:59], v[64:67], v[112:115], v[56:59]
	s_waitcnt lgkmcnt(2)
	v_mfma_f32_16x16x32_bf16 v[64:67], v[68:71], v[116:119], v[44:47]
	v_mfma_f32_16x16x32_bf16 v[72:75], v[68:71], v[124:127], v[48:51]
	s_waitcnt lgkmcnt(0)
	v_mfma_f32_16x16x32_bf16 v[60:63], v[120:123], v[116:119], v[52:55]
	v_mfma_f32_16x16x32_bf16 v[68:71], v[120:123], v[124:127], v[56:59]
	ds_read_b64_tr_b16 v[44:45], v208 offset:53312
	ds_read_b64_tr_b16 v[48:49], v208 offset:53344
	ds_read_b64_tr_b16 v[46:47], v208 offset:57920
	ds_read_b64_tr_b16 v[50:51], v208 offset:57952
	ds_read_b64_tr_b16 v[52:53], v208 offset:62528
	ds_read_b64_tr_b16 v[54:55], v211 offset:4608
	ds_read_b64_tr_b16 v[58:59], v212 offset:4608
	ds_read_b64_tr_b16 v[56:57], v208 offset:62560
	s_waitcnt lgkmcnt(5)
	v_mfma_f32_16x16x32_bf16 v[84:87], v[44:47], v[108:111], v[84:87]
	v_mfma_f32_16x16x32_bf16 v[44:47], v[44:47], v[112:115], v[88:91]
	s_waitcnt lgkmcnt(4)
	v_mfma_f32_16x16x32_bf16 v[92:95], v[48:51], v[108:111], v[92:95]
	v_mfma_f32_16x16x32_bf16 v[48:51], v[48:51], v[112:115], v[100:103]
	s_waitcnt lgkmcnt(2)
	v_mfma_f32_16x16x32_bf16 v[88:91], v[52:55], v[116:119], v[84:87]
	v_mfma_f32_16x16x32_bf16 v[100:103], v[52:55], v[124:127], v[44:47]
	s_waitcnt lgkmcnt(0)
	v_mfma_f32_16x16x32_bf16 v[84:87], v[56:59], v[116:119], v[92:95]
	v_mfma_f32_16x16x32_bf16 v[92:95], v[56:59], v[124:127], v[48:51]
	v_mov_b64_e32 v[52:53], v[104:105]
	s_nop 0
	v_mov_b64_e32 v[48:49], v[96:97]
	v_mov_b64_e32 v[44:45], v[76:77]
	v_mov_b64_e32 v[56:57], v[80:81]
	v_mov_b64_e32 v[54:55], v[106:107]
	v_mov_b64_e32 v[50:51], v[98:99]
	v_mov_b64_e32 v[46:47], v[78:79]
	v_mov_b64_e32 v[58:59], v[82:83]

; #define LAS __attribute__((address_space(3)))
; DI float fast_exp2(float x) { return __builtin_amdgcn_exp2f(x); }
; #define MFMA16(a, b, c) __builtin_amdgcn_mfma_f32_16x16x32_bf16((a), (b), (c), 0, 0, 0)
; DI void at_qk(f32x4 (&s1)[4], f32x4 (&s2)[4], const LAS unsigned char* buf, const bf16x8 q1, const bf16x8 q2, const f32x4 (&ci)[4], int hh, int fr, int fq) {
; #pragma unroll
;     for (int k4 = 0; k4 < 4; ++k4) { const LAS unsigned char* kr = buf + AT_K + (16 * k4 + fr) * 272 + hh * 128 + fq * 16;
;         s1[k4] = MFMA16(ld8l(kr), q1, ci[k4]); s2[k4] = MFMA16(ld8l(kr + 64), q2, ci[k4]); }
; }
; DI void at_exp(f32x4 (&s1)[4], f32x4 (&s2)[4], float& ps1, float& ps2) {
;     f32x4 a1 = (f32x4){0.f, 0.f, 0.f, 0.f}, a2 = a1;
; #pragma unroll
;     for (int k4 = 0; k4 < 4; ++k4) {
; #pragma unroll
;         for (int j = 0; j < 4; ++j) { s1[k4][j] = fast_exp2(s1[k4][j]); s2[k4][j] = fast_exp2(s2[k4][j]); }
;         a1 = a1 + s1[k4]; a2 = a2 + s2[k4]; }
;     ps1 = (a1[0] + a1[1]) + (a1[2] + a1[3]); ps2 = (a2[0] + a2[1]) + (a2[2] + a2[3]);
; }
; template <int VAR>
; DI void attn_tile(AtState& S, const LAS unsigned char* buf, const bf16x8 q1, const bf16x8 q2, int kt, bool diag, int qpos0, int qpos_l, float slope2, float adv, float decay, int hh, int fr, int fq) {
;     ...
;         asm volatile("; attention: fast tile" ::: "memory");
;         at_qk(s1, s2, buf, q1, q2, S.cinit, hh, fr, fq);
;         S.ref += adv;
;         at_exp(s1, s2, ps1, ps2);
;         if (__any(!(ps1 + ps2 < 0x1p60f))) {
;             asm volatile("; attention: bump" ::: "memory");
;             at_qk(s1, s2, buf, q1, q2, S.cinit, hh, fr, fq);
;             float lm = -1e30f;
; #pragma unroll
;             for (int k4 = 0; k4 < 4; ++k4)
; #pragma unroll
;                 for (int j = 0; j < 4; ++j) lm = fmaxf(lm, fmaxf(s1[k4][j], s2[k4][j]));
;             lm = fmaxf(lm, __shfl_xor(lm, 16)); lm = fmaxf(lm, __shfl_xor(lm, 32));
.LBB0_1405:
	s_bitcmp1_b32 s40, 0
	s_cselect_b32 s26, 0x8c00, 0
	s_add_i32 s28, s41, s26
	s_sub_i32 s27, s40, 32
	v_add_u32_e32 v3, s28, v206
	s_cmp_gt_u32 s27, 0xffffffe0
	s_mov_b64 s[26:27], -1
	v_add_u32_e32 v3, v3, v207
	s_cbranch_scc0 .LBB0_1410
	ds_read_b128 v[62:65], v3
	ds_read_b128 v[66:69], v3 offset:64
	ds_read_b128 v[70:73], v3 offset:4352
	ds_read_b128 v[74:77], v3 offset:4416
	ds_read_b128 v[78:81], v3 offset:8704
	ds_read_b128 v[82:85], v3 offset:8768
	ds_read_b128 v[86:89], v3 offset:13056
	ds_read_b128 v[90:93], v3 offset:13120
	s_waitcnt lgkmcnt(7)
	v_mfma_f32_16x16x32_bf16 v[62:65], v[62:65], v[38:41], v[46:49]
	v_add_f32_e32 v213, v204, v212
	s_waitcnt lgkmcnt(6)
	v_mfma_f32_16x16x32_bf16 v[66:69], v[66:69], v[42:45], v[46:49]
	s_waitcnt lgkmcnt(5)
	v_mfma_f32_16x16x32_bf16 v[70:73], v[70:73], v[38:41], v[50:53]
	s_nop 2
	v_exp_f32_e32 v164, v62
	v_exp_f32_e32 v165, v63
	v_exp_f32_e32 v168, v64
	s_waitcnt lgkmcnt(4)
	v_mfma_f32_16x16x32_bf16 v[74:77], v[74:77], v[42:45], v[50:53]
	v_exp_f32_e32 v169, v65
	v_exp_f32_e32 v162, v66
	v_exp_f32_e32 v163, v67
	s_waitcnt lgkmcnt(3)
	v_mfma_f32_16x16x32_bf16 v[78:81], v[78:81], v[38:41], v[54:57]
	v_exp_f32_e32 v166, v68
	v_exp_f32_e32 v167, v69
	v_exp_f32_e32 v172, v70
	s_waitcnt lgkmcnt(2)
	v_mfma_f32_16x16x32_bf16 v[62:65], v[82:85], v[42:45], v[54:57]
	v_exp_f32_e32 v170, v74
	v_exp_f32_e32 v173, v71
	v_exp_f32_e32 v176, v72
	s_waitcnt lgkmcnt(1)
	v_mfma_f32_16x16x32_bf16 v[66:69], v[86:89], v[38:41], v[58:61]
	v_exp_f32_e32 v177, v73
	v_exp_f32_e32 v174, v76
	v_exp_f32_e32 v175, v77
	s_waitcnt lgkmcnt(0)
	v_mfma_f32_16x16x32_bf16 v[82:85], v[90:93], v[42:45], v[58:61]
	v_exp_f32_e32 v171, v75
	v_exp_f32_e32 v180, v78
	v_exp_f32_e32 v178, v62
	v_exp_f32_e32 v181, v79
	v_exp_f32_e32 v179, v63
	v_exp_f32_e32 v184, v80
	v_exp_f32_e32 v185, v81
	v_exp_f32_e32 v182, v64
	v_exp_f32_e32 v183, v65
	v_exp_f32_e32 v188, v66
	v_exp_f32_e32 v186, v82
	v_exp_f32_e32 v189, v67
	v_exp_f32_e32 v192, v68
	v_exp_f32_e32 v193, v69
	v_exp_f32_e32 v190, v84
	v_exp_f32_e32 v191, v85
	v_exp_f32_e32 v187, v83
	v_pk_add_f32 v[70:71], v[168:169], v[176:177]
	v_pk_add_f32 v[72:73], v[164:165], v[172:173]
	v_pk_add_f32 v[74:75], v[166:167], v[174:175]
	v_pk_add_f32 v[76:77], v[162:163], v[170:171]
	v_pk_add_f32 v[62:63], v[72:73], v[180:181]
	v_pk_add_f32 v[64:65], v[70:71], v[184:185]
	v_pk_add_f32 v[70:71], v[76:77], v[178:179]
	v_pk_add_f32 v[72:73], v[74:75], v[182:183]
	v_pk_add_f32 v[64:65], v[64:65], v[192:193]
	v_pk_add_f32 v[62:63], v[62:63], v[188:189]
	v_pk_add_f32 v[66:67], v[72:73], v[190:191]
	v_pk_add_f32 v[68:69], v[70:71], v[186:187]
	v_mov_b32_e32 v71, v62
	v_mov_b32_e32 v70, v68
	v_mov_b32_e32 v62, v69
	v_mov_b32_e32 v68, v66
	v_mov_b32_e32 v69, v64
	v_mov_b32_e32 v64, v67
	v_pk_add_f32 v[62:63], v[70:71], v[62:63]
	v_pk_add_f32 v[64:65], v[68:69], v[64:65]
	s_nop 0
	v_pk_add_f32 v[194:195], v[62:63], v[64:65]
	s_nop 0
	v_add_f32_e32 v62, v195, v194
	v_cmp_ngt_f32_e32 vcc, s65, v62
	s_cbranch_vccz .LBB0_1416
	ds_read_b128 v[62:65], v3
	ds_read_b128 v[66:69], v3 offset:64
	ds_read_b128 v[70:73], v3 offset:4352
	ds_read_b128 v[74:77], v3 offset:4416
	ds_read_b128 v[78:81], v3 offset:8704
	ds_read_b128 v[82:85], v3 offset:8768
	ds_read_b128 v[86:89], v3 offset:13056
	ds_read_b128 v[90:93], v3 offset:13120
	v_add3_u32 v246, s28, v208, v209
	s_waitcnt lgkmcnt(7)
	v_mfma_f32_16x16x32_bf16 v[62:65], v[62:65], v[38:41], v[46:49]
	s_waitcnt lgkmcnt(6)
	v_mfma_f32_16x16x32_bf16 v[66:69], v[66:69], v[42:45], v[46:49]
	s_waitcnt lgkmcnt(5)
	v_mfma_f32_16x16x32_bf16 v[70:73], v[70:73], v[38:41], v[50:53]
	s_waitcnt lgkmcnt(4)
	v_mfma_f32_16x16x32_bf16 v[74:77], v[74:77], v[42:45], v[50:53]
	s_waitcnt lgkmcnt(3)
	v_mfma_f32_16x16x32_bf16 v[78:81], v[78:81], v[38:41], v[54:57]
	s_waitcnt lgkmcnt(2)
	v_mfma_f32_16x16x32_bf16 v[82:85], v[82:85], v[42:45], v[54:57]
	s_waitcnt lgkmcnt(1)
	v_mfma_f32_16x16x32_bf16 v[86:89], v[86:89], v[38:41], v[58:61]
	s_waitcnt lgkmcnt(0)
	v_mfma_f32_16x16x32_bf16 v[90:93], v[90:93], v[42:45], v[58:61]
	v_max3_f32 v94, v62, v66, s60
	v_max3_f32 v94, v94, v63, v67
	v_max3_f32 v94, v94, v64, v68
	v_max3_f32 v94, v94, v65, v69
	v_max3_f32 v94, v94, v70, v74
	v_max3_f32 v94, v94, v71, v75
	v_max3_f32 v94, v94, v72, v76
	v_max3_f32 v94, v94, v73, v77
	v_max3_f32 v94, v94, v78, v82
	v_max3_f32 v94, v94, v79, v83
	v_max3_f32 v94, v94, v80, v84
	v_max3_f32 v94, v94, v81, v85
	v_max3_f32 v94, v94, v86, v90
	v_max3_f32 v94, v94, v87, v91
	v_max3_f32 v94, v94, v88, v92
	v_max3_f32 v94, v94, v89, v93
	v_and_b32_e32 v96, 64, v198
	v_mov_b32_e32 v95, v94
	v_mov_b32_e32 v255, v94
	s_nop 1
	v_permlane16_swap_b32_e32 v95, v255
	s_waitcnt lgkmcnt(0)
	v_max_f32_e32 v94, v95, v255
	v_mov_b32_e32 v95, v94
	v_mov_b32_e32 v255, v94
	s_nop 1
	v_permlane32_swap_b32_e32 v95, v255
	s_waitcnt lgkmcnt(0)
; #define LAS __attribute__((address_space(3)))
; DI float fast_exp2(float x) { return __builtin_amdgcn_exp2f(x); }
; #define MFMA16(a, b, c) __builtin_amdgcn_mfma_f32_16x16x32_bf16((a), (b), (c), 0, 0, 0)
; DI u32x2 tr4(const LAS unsigned char* p) { return __builtin_bit_cast(u32x2, __builtin_amdgcn_ds_read_tr16_b64_v4i16((LAS v4i16_t*)p)); }
; DI bf16x8 packp(f32x4 a, f32x4 b) { return __builtin_bit_cast(bf16x8, pack8(a, b)); }
; DI void at_pv(AtState& S, const f32x4 (&s1)[4], const f32x4 (&s2)[4], float alpha, float ps1, float ps2, const LAS unsigned char* buf, int hh, int fq, int tq, int tp) {
;     S.l1 = S.l1 * alpha + ps1; S.l2 = S.l2 * alpha + ps2;
; #pragma unroll
;     for (int dt = 0; dt < 4; ++dt) { S.O1[dt] = S.O1[dt] * alpha; S.O2[dt] = S.O2[dt] * alpha; }
;     bf16x8 p1[2], p2[2];
; #pragma unroll
;     for (int s = 0; s < 2; ++s) { p1[s] = packp(s1[2 * s], s1[2 * s + 1]); p2[s] = packp(s2[2 * s], s2[2 * s + 1]); }
; #pragma unroll
;     for (int dh = 0; dh < 2; ++dh) {
;         bf16x8 vt[2][2];
; #pragma unroll
;         for (int d2 = 0; d2 < 2; ++d2)
; #pragma unroll
;             for (int s = 0; s < 2; ++s) { const int dt = 2 * dh + d2; const LAS unsigned char* vr = buf + AT_V + (32 * s + 4 * fq + tq) * 288 + (hh * 64 + 16 * dt + 4 * tp) * 2; vt[d2][s] = cat44(tr4(vr), tr4(vr + 16 * 288)); }
;         __builtin_amdgcn_s_setprio(1);
; #pragma unroll
;         for (int s = 0; s < 2; ++s)
; #pragma unroll
;             for (int d2 = 0; d2 < 2; ++d2) { const int dt = 2 * dh + d2; S.O1[dt] = MFMA16(vt[d2][s], p1[s], S.O1[dt]); S.O2[dt] = MFMA16(vt[d2][s], p2[s], S.O2[dt]); }
;         __builtin_amdgcn_s_setprio(0);
;         __builtin_amdgcn_sched_barrier(0);
;     }
; }
; template <int VAR>
; DI void attn_tile(AtState& S, const LAS unsigned char* buf, const bf16x8 q1, const bf16x8 q2, int kt, bool diag, int qpos0, int qpos_l, float slope2, float adv, float decay, int hh, int fr, int fq) {
;     ...
;             const float bump = fmaxf(lm, 0.f);
;             const float alpha = decay * fast_exp2(-bump); S.ref += bump;
; #pragma unroll
;             for (int k4 = 0; k4 < 4; ++k4) { s1[k4] = s1[k4] - bump; s2[k4] = s2[k4] - bump; S.cinit[k4] = S.cinit[k4] - bump; }
;             at_exp(s1, s2, ps1, ps2);
;             at_pv(S, s1, s2, alpha, ps1, ps2, buf, hh, fq, tq, tp);
	v_max3_f32 v94, v255, v95, 0
	v_sub_f32_e32 v96, v65, v94
	v_sub_f32_e32 v97, v64, v94
	v_sub_f32_e32 v98, v63, v94
	v_sub_f32_e32 v99, v62, v94
	v_sub_f32_e32 v69, v69, v94
	v_sub_f32_e32 v68, v68, v94
	v_sub_f32_e32 v67, v67, v94
	v_sub_f32_e32 v66, v66, v94
	v_sub_f32_e32 v100, v73, v94
	v_sub_f32_e32 v101, v72, v94
	v_sub_f32_e32 v102, v71, v94
	v_sub_f32_e32 v103, v70, v94
	v_sub_f32_e32 v104, v77, v94
	v_sub_f32_e32 v105, v76, v94
	v_sub_f32_e32 v107, v75, v94
	v_sub_f32_e32 v108, v74, v94
	v_exp_f32_e32 v214, v99
	v_exp_f32_e32 v218, v66
	v_exp_f32_e32 v215, v98
	v_exp_f32_e32 v219, v67
	v_exp_f32_e32 v216, v97
	v_exp_f32_e32 v220, v68
	v_exp_f32_e32 v217, v96
	v_exp_f32_e32 v221, v69
	v_sub_f32_e32 v109, v81, v94
	v_sub_f32_e32 v158, v80, v94
	v_sub_f32_e32 v159, v79, v94
	v_sub_f32_e32 v230, v78, v94
	v_sub_f32_e32 v85, v85, v94
	v_sub_f32_e32 v84, v84, v94
	v_sub_f32_e32 v83, v83, v94
	v_sub_f32_e32 v82, v82, v94
	v_exp_f32_e32 v222, v103
	v_exp_f32_e32 v224, v108
	v_exp_f32_e32 v223, v102
	v_exp_f32_e32 v225, v107
	v_exp_f32_e32 v226, v101
	v_exp_f32_e32 v228, v105
	v_exp_f32_e32 v227, v100
	v_exp_f32_e32 v229, v104
	v_sub_f32_e32 v89, v89, v94
	v_sub_f32_e32 v88, v88, v94
	v_sub_f32_e32 v87, v87, v94
	v_sub_f32_e32 v86, v86, v94
	v_sub_f32_e32 v245, v93, v94
	v_sub_f32_e32 v243, v92, v94
	v_sub_f32_e32 v241, v91, v94
	v_sub_f32_e32 v239, v90, v94
	v_exp_f32_e32 v230, v230
	v_exp_f32_e32 v232, v82
	v_exp_f32_e32 v231, v159
	v_exp_f32_e32 v233, v83
	v_exp_f32_e32 v234, v158
	v_exp_f32_e32 v236, v84
	v_exp_f32_e32 v235, v109
	v_exp_f32_e32 v237, v85
	v_exp_f32_e32 v238, v86
	v_exp_f32_e32 v240, v239
	v_exp_f32_e32 v239, v87
	v_exp_f32_e32 v241, v241
	v_exp_f32_e32 v242, v88
	v_exp_f32_e32 v244, v243
	v_exp_f32_e32 v243, v89
	v_exp_f32_e32 v245, v245
	v_pk_add_f32 v[68:69], v[226:227], v[216:217]
	v_pk_add_f32 v[66:67], v[222:223], v[214:215]
	v_pk_add_f32 v[72:73], v[228:229], v[220:221]
	v_pk_add_f32 v[70:71], v[224:225], v[218:219]
	v_pk_add_f32 v[66:67], v[230:231], v[66:67]
	v_pk_add_f32 v[68:69], v[234:235], v[68:69]
	v_pk_add_f32 v[70:71], v[232:233], v[70:71]
	v_pk_add_f32 v[72:73], v[236:237], v[72:73]
	v_pk_add_f32 v[68:69], v[242:243], v[68:69]
	v_pk_add_f32 v[66:67], v[238:239], v[66:67]
	v_pk_add_f32 v[72:73], v[244:245], v[72:73]
	v_pk_add_f32 v[70:71], v[240:241], v[70:71]
	v_cvt_pk_bf16_f32 v214, v214, v215
	v_cvt_pk_bf16_f32 v215, v216, v217
	v_cvt_pk_bf16_f32 v216, v222, v223
	v_cvt_pk_bf16_f32 v217, v226, v227
	v_cvt_pk_bf16_f32 v218, v218, v219
	v_cvt_pk_bf16_f32 v219, v220, v221
	v_cvt_pk_bf16_f32 v220, v224, v225
	v_cvt_pk_bf16_f32 v221, v228, v229
	v_cvt_pk_bf16_f32 v222, v230, v231
	v_cvt_pk_bf16_f32 v223, v234, v235
	v_cvt_pk_bf16_f32 v224, v238, v239
	v_cvt_pk_bf16_f32 v225, v242, v243
	v_cvt_pk_bf16_f32 v226, v232, v233
	v_cvt_pk_bf16_f32 v227, v236, v237
	v_cvt_pk_bf16_f32 v228, v240, v241
	v_cvt_pk_bf16_f32 v229, v244, v245
	ds_read_b64_tr_b16 v[230:231], v246 offset:17408
	ds_read_b64_tr_b16 v[234:235], v246 offset:17440
	ds_read_b64_tr_b16 v[232:233], v246 offset:22016
	ds_read_b64_tr_b16 v[238:239], v246 offset:26624
	ds_read_b64_tr_b16 v[240:241], v246 offset:31232
	ds_read_b64_tr_b16 v[236:237], v246 offset:22048
	ds_read_b64_tr_b16 v[242:243], v246 offset:26656
	ds_read_b64_tr_b16 v[244:245], v246 offset:31264
	v_exp_f32_e64 v95, -v94
	v_mov_b32_e32 v82, v70
	v_mov_b32_e32 v83, v66
	v_mov_b32_e32 v66, v71
	v_mov_b32_e32 v70, v72
	v_mov_b32_e32 v71, v68
	v_mov_b32_e32 v68, v73
	v_pk_add_f32 v[66:67], v[82:83], v[66:67]
	v_pk_add_f32 v[68:69], v[70:71], v[68:69]
	v_mul_f32_e32 v106, v116, v95
	v_pk_add_f32 v[66:67], v[66:67], v[68:69]
	v_add_f32_e32 v117, v213, v94
	v_sub_f32_e32 v65, v49, v94
	v_sub_f32_e32 v64, v48, v94
	v_sub_f32_e32 v63, v47, v94
	v_sub_f32_e32 v62, v46, v94
	v_sub_f32_e32 v77, v53, v94
	v_sub_f32_e32 v76, v52, v94
	v_sub_f32_e32 v75, v51, v94
	v_sub_f32_e32 v74, v50, v94
	v_sub_f32_e32 v81, v57, v94
	v_sub_f32_e32 v80, v56, v94
	v_sub_f32_e32 v79, v55, v94
	v_sub_f32_e32 v78, v54, v94
	v_sub_f32_e32 v93, v61, v94
	v_sub_f32_e32 v92, v60, v94
	v_sub_f32_e32 v91, v59, v94
	v_sub_f32_e32 v90, v58, v94
	v_pk_fma_f32 v[158:159], v[156:157], v[106:107], v[66:67] op_sel_hi:[1,0,1]
	v_pk_mul_f32 v[68:69], v[154:155], v[106:107] op_sel_hi:[1,0]
	v_pk_mul_f32 v[66:67], v[152:153], v[106:107] op_sel_hi:[1,0]
	v_pk_mul_f32 v[72:73], v[150:151], v[106:107] op_sel_hi:[1,0]
	v_pk_mul_f32 v[70:71], v[148:149], v[106:107] op_sel_hi:[1,0]
	v_pk_mul_f32 v[84:85], v[146:147], v[106:107] op_sel_hi:[1,0]
	v_pk_mul_f32 v[82:83], v[144:145], v[106:107] op_sel_hi:[1,0]
	v_pk_mul_f32 v[88:89], v[138:139], v[106:107] op_sel_hi:[1,0]
	v_pk_mul_f32 v[86:87], v[136:137], v[106:107] op_sel_hi:[1,0]
	v_pk_mul_f32 v[96:97], v[134:135], v[106:107] op_sel_hi:[1,0]
	v_pk_mul_f32 v[94:95], v[132:133], v[106:107] op_sel_hi:[1,0]
	v_pk_mul_f32 v[100:101], v[130:131], v[106:107] op_sel_hi:[1,0]
	v_pk_mul_f32 v[98:99], v[128:129], v[106:107] op_sel_hi:[1,0]
	v_pk_mul_f32 v[104:105], v[126:127], v[106:107] op_sel_hi:[1,0]
	v_pk_mul_f32 v[102:103], v[124:125], v[106:107] op_sel_hi:[1,0]
	v_pk_mul_f32 v[108:109], v[4:5], v[106:107] op_sel_hi:[1,0]
	v_pk_mul_f32 v[106:107], v[122:123], v[106:107] op_sel_hi:[1,0]
	s_waitcnt lgkmcnt(5)
	v_mfma_f32_16x16x32_bf16 v[66:69], v[230:233], v[214:217], v[66:69]
	v_mfma_f32_16x16x32_bf16 v[70:73], v[230:233], v[218:221], v[70:73]
	s_waitcnt lgkmcnt(2)
	v_mfma_f32_16x16x32_bf16 v[82:85], v[234:237], v[214:217], v[82:85]
	v_mfma_f32_16x16x32_bf16 v[230:233], v[234:237], v[218:221], v[86:89]
	v_mfma_f32_16x16x32_bf16 v[66:69], v[238:241], v[222:225], v[66:69]
	v_mfma_f32_16x16x32_bf16 v[86:89], v[238:241], v[226:229], v[70:73]
	s_waitcnt lgkmcnt(0)
	v_mfma_f32_16x16x32_bf16 v[70:73], v[242:245], v[222:225], v[82:85]
	v_mfma_f32_16x16x32_bf16 v[82:85], v[242:245], v[226:229], v[230:233]
	s_nop 1
	ds_read_b64_tr_b16 v[230:231], v246 offset:17472
	ds_read_b64_tr_b16 v[234:235], v246 offset:17504
	ds_read_b64_tr_b16 v[232:233], v246 offset:22080
	ds_read_b64_tr_b16 v[236:237], v246 offset:22112
	ds_read_b64_tr_b16 v[238:239], v246 offset:26688
	ds_read_b64_tr_b16 v[240:241], v246 offset:31296
	ds_read_b64_tr_b16 v[244:245], v246 offset:31328
	ds_read_b64_tr_b16 v[242:243], v246 offset:26720
	s_waitcnt lgkmcnt(5)
	v_mfma_f32_16x16x32_bf16 v[94:97], v[230:233], v[214:217], v[94:97]
	v_mfma_f32_16x16x32_bf16 v[98:101], v[230:233], v[218:221], v[98:101]
	s_waitcnt lgkmcnt(4)
	v_mfma_f32_16x16x32_bf16 v[102:105], v[234:237], v[214:217], v[102:105]
	v_mfma_f32_16x16x32_bf16 v[214:217], v[234:237], v[218:221], v[106:109]
	s_waitcnt lgkmcnt(2)
	v_mfma_f32_16x16x32_bf16 v[94:97], v[238:241], v[222:225], v[94:97]
	v_mfma_f32_16x16x32_bf16 v[106:109], v[238:241], v[226:229], v[98:101]
	s_waitcnt lgkmcnt(0)
	v_mfma_f32_16x16x32_bf16 v[98:101], v[242:245], v[222:225], v[102:105]
	v_mfma_f32_16x16x32_bf16 v[102:105], v[242:245], v[226:229], v[214:217]
	s_cbranch_execnz .LBB0_1409
; #define LAS __attribute__((address_space(3)))
; #define MFMA16(a, b, c) __builtin_amdgcn_mfma_f32_16x16x32_bf16((a), (b), (c), 0, 0, 0)
; DI u32x2 tr4(const LAS unsigned char* p) { return __builtin_bit_cast(u32x2, __builtin_amdgcn_ds_read_tr16_b64_v4i16((LAS v4i16_t*)p)); }
; DI bf16x8 packp(f32x4 a, f32x4 b) { return __builtin_bit_cast(bf16x8, pack8(a, b)); }
; DI void at_pv(AtState& S, const f32x4 (&s1)[4], const f32x4 (&s2)[4], float alpha, float ps1, float ps2, const LAS unsigned char* buf, int hh, int fq, int tq, int tp) {
;     S.l1 = S.l1 * alpha + ps1; S.l2 = S.l2 * alpha + ps2;
; #pragma unroll
;     for (int dt = 0; dt < 4; ++dt) { S.O1[dt] = S.O1[dt] * alpha; S.O2[dt] = S.O2[dt] * alpha; }
;     bf16x8 p1[2], p2[2];
; #pragma unroll
;     for (int s = 0; s < 2; ++s) { p1[s] = packp(s1[2 * s], s1[2 * s + 1]); p2[s] = packp(s2[2 * s], s2[2 * s + 1]); }
; #pragma unroll
;     for (int dh = 0; dh < 2; ++dh) {
;         bf16x8 vt[2][2];
; #pragma unroll
;         for (int d2 = 0; d2 < 2; ++d2)
; #pragma unroll
;             for (int s = 0; s < 2; ++s) { const int dt = 2 * dh + d2; const LAS unsigned char* vr = buf + AT_V + (32 * s + 4 * fq + tq) * 288 + (hh * 64 + 16 * dt + 4 * tp) * 2; vt[d2][s] = cat44(tr4(vr), tr4(vr + 16 * 288)); }
;         __builtin_amdgcn_s_setprio(1);
; #pragma unroll
;         for (int s = 0; s < 2; ++s)
; #pragma unroll
;             for (int d2 = 0; d2 < 2; ++d2) { const int dt = 2 * dh + d2; S.O1[dt] = MFMA16(vt[d2][s], p1[s], S.O1[dt]); S.O2[dt] = MFMA16(vt[d2][s], p2[s], S.O2[dt]); }
;         __builtin_amdgcn_s_setprio(0);
;         __builtin_amdgcn_sched_barrier(0);
;     }
; }
; template <int VAR>
; DI void attn_tile(AtState& S, const LAS unsigned char* buf, const bf16x8 q1, const bf16x8 q2, int kt, bool diag, int qpos0, int qpos_l, float slope2, float adv, float decay, int hh, int fr, int fq) {
;     ...
;             asm volatile("; attention: fast tail" ::: "memory");
;             at_pv(S, s1, s2, decay, ps1, ps2, buf, hh, fq, tq, tp);
.LBB0_1408:
	v_mov_b32_e32 v117, v116
	v_pk_mul_f32 v[64:65], v[116:117], v[154:155]
	v_pk_mul_f32 v[68:69], v[116:117], v[150:151]
	v_pk_mul_f32 v[72:73], v[116:117], v[146:147]
	v_pk_mul_f32 v[76:77], v[116:117], v[138:139]
	v_pk_mul_f32 v[80:81], v[116:117], v[134:135]
	v_pk_mul_f32 v[92:93], v[116:117], v[130:131]
	v_pk_mul_f32 v[96:97], v[116:117], v[126:127]
	v_pk_mul_f32 v[100:101], v[116:117], v[4:5]
	v_add3_u32 v117, s28, v208, v209
	v_cvt_pk_bf16_f32 v104, v172, v173
	v_cvt_pk_bf16_f32 v105, v176, v177
	v_cvt_pk_bf16_f32 v108, v170, v171
	v_cvt_pk_bf16_f32 v109, v174, v175
	ds_read_b64_tr_b16 v[82:83], v117 offset:17408
	ds_read_b64_tr_b16 v[86:87], v117 offset:17440
	ds_read_b64_tr_b16 v[84:85], v117 offset:22016
	ds_read_b64_tr_b16 v[170:171], v117 offset:26624
	ds_read_b64_tr_b16 v[172:173], v117 offset:31232
	ds_read_b64_tr_b16 v[88:89], v117 offset:22048
	ds_read_b64_tr_b16 v[174:175], v117 offset:26656
	ds_read_b64_tr_b16 v[176:177], v117 offset:31264
	v_pk_fma_f32 v[158:159], v[120:121], v[156:157], v[194:195]
	v_pk_mul_f32 v[62:63], v[118:119], v[152:153]
	v_pk_mul_f32 v[66:67], v[118:119], v[148:149]
	v_pk_mul_f32 v[70:71], v[118:119], v[144:145]
	v_pk_mul_f32 v[74:75], v[118:119], v[136:137]
	v_pk_mul_f32 v[78:79], v[118:119], v[132:133]
	v_pk_mul_f32 v[90:91], v[118:119], v[128:129]
	v_pk_mul_f32 v[94:95], v[118:119], v[124:125]
	v_pk_mul_f32 v[98:99], v[118:119], v[122:123]
	v_cvt_pk_bf16_f32 v102, v164, v165
	v_cvt_pk_bf16_f32 v103, v168, v169
	v_cvt_pk_bf16_f32 v106, v162, v163
	v_cvt_pk_bf16_f32 v107, v166, v167
	v_cvt_pk_bf16_f32 v162, v180, v181
	v_cvt_pk_bf16_f32 v163, v184, v185
	v_cvt_pk_bf16_f32 v164, v188, v189
	v_cvt_pk_bf16_f32 v165, v192, v193
	v_cvt_pk_bf16_f32 v166, v178, v179
	v_cvt_pk_bf16_f32 v167, v182, v183
	v_cvt_pk_bf16_f32 v168, v186, v187
	v_cvt_pk_bf16_f32 v169, v190, v191
	s_waitcnt lgkmcnt(5)
	v_mfma_f32_16x16x32_bf16 v[62:65], v[82:85], v[102:105], v[62:65]
	v_mfma_f32_16x16x32_bf16 v[82:85], v[82:85], v[106:109], v[66:69]
	s_waitcnt lgkmcnt(2)
	v_mfma_f32_16x16x32_bf16 v[70:73], v[86:89], v[102:105], v[70:73]
	v_mfma_f32_16x16x32_bf16 v[74:77], v[86:89], v[106:109], v[74:77]
	v_mfma_f32_16x16x32_bf16 v[66:69], v[170:173], v[162:165], v[62:65]
	v_mfma_f32_16x16x32_bf16 v[86:89], v[170:173], v[166:169], v[82:85]
	s_waitcnt lgkmcnt(0)
	v_mfma_f32_16x16x32_bf16 v[70:73], v[174:177], v[162:165], v[70:73]
	v_mfma_f32_16x16x32_bf16 v[82:85], v[174:177], v[166:169], v[74:77]
	ds_read_b64_tr_b16 v[62:63], v117 offset:17472
	s_nop 0
	ds_read_b64_tr_b16 v[74:75], v117 offset:17504
	ds_read_b64_tr_b16 v[64:65], v117 offset:22080
	ds_read_b64_tr_b16 v[76:77], v117 offset:22112
	ds_read_b64_tr_b16 v[170:171], v117 offset:26688
	ds_read_b64_tr_b16 v[172:173], v117 offset:31296
	ds_read_b64_tr_b16 v[176:177], v117 offset:31328
	ds_read_b64_tr_b16 v[174:175], v117 offset:26720
	s_waitcnt lgkmcnt(5)
	v_mfma_f32_16x16x32_bf16 v[78:81], v[62:65], v[102:105], v[78:81]
	v_mfma_f32_16x16x32_bf16 v[62:65], v[62:65], v[106:109], v[90:93]
	s_waitcnt lgkmcnt(4)
	v_mfma_f32_16x16x32_bf16 v[90:93], v[74:77], v[102:105], v[94:97]
	v_mfma_f32_16x16x32_bf16 v[74:77], v[74:77], v[106:109], v[98:101]
	s_waitcnt lgkmcnt(2)
	v_mfma_f32_16x16x32_bf16 v[94:97], v[170:173], v[162:165], v[78:81]
	v_mfma_f32_16x16x32_bf16 v[106:109], v[170:173], v[166:169], v[62:65]
	s_waitcnt lgkmcnt(0)
	v_mfma_f32_16x16x32_bf16 v[98:101], v[174:177], v[162:165], v[90:93]
	v_mfma_f32_16x16x32_bf16 v[102:105], v[174:177], v[166:169], v[74:77]
	v_mov_b64_e32 v[64:65], v[48:49]
	s_nop 0
	v_mov_b64_e32 v[76:77], v[52:53]
	v_mov_b64_e32 v[80:81], v[56:57]
	v_mov_b64_e32 v[92:93], v[60:61]
	v_mov_b32_e32 v117, v213
	v_mov_b64_e32 v[62:63], v[46:47]
	v_mov_b64_e32 v[74:75], v[50:51]
	v_mov_b64_e32 v[78:79], v[54:55]
	v_mov_b64_e32 v[90:91], v[58:59]

; #define LAS __attribute__((address_space(3)))
; DI float fast_exp2(float x) { return __builtin_amdgcn_exp2f(x); }
; #define MFMA16(a, b, c) __builtin_amdgcn_mfma_f32_16x16x32_bf16((a), (b), (c), 0, 0, 0)
; DI bf16x8 packp(f32x4 a, f32x4 b) { return __builtin_bit_cast(bf16x8, pack8(a, b)); }
; DI void at_pv(AtState& S, const f32x4 (&s1)[4], const f32x4 (&s2)[4], float alpha, float ps1, float ps2, const LAS unsigned char* buf, int hh, int fq, int tq, int tp) {
;     S.l1 = S.l1 * alpha + ps1; S.l2 = S.l2 * alpha + ps2;
; #pragma unroll
;     for (int dt = 0; dt < 4; ++dt) { S.O1[dt] = S.O1[dt] * alpha; S.O2[dt] = S.O2[dt] * alpha; }
;     bf16x8 p1[2], p2[2];
; #pragma unroll
;     for (int s = 0; s < 2; ++s) { p1[s] = packp(s1[2 * s], s1[2 * s + 1]); p2[s] = packp(s2[2 * s], s2[2 * s + 1]); }
; #pragma unroll
;     for (int dh = 0; dh < 2; ++dh) {
;         bf16x8 vt[2][2];
; #pragma unroll
;         for (int d2 = 0; d2 < 2; ++d2)
; #pragma unroll
;             for (int s = 0; s < 2; ++s) { const int dt = 2 * dh + d2; const LAS unsigned char* vr = buf + AT_V + (32 * s + 4 * fq + tq) * 288 + (hh * 64 + 16 * dt + 4 * tp) * 2; vt[d2][s] = cat44(tr4(vr), tr4(vr + 16 * 288)); }
;         __builtin_amdgcn_s_setprio(1);
; #pragma unroll
;         for (int s = 0; s < 2; ++s)
; #pragma unroll
;             for (int d2 = 0; d2 < 2; ++d2) { const int dt = 2 * dh + d2; S.O1[dt] = MFMA16(vt[d2][s], p1[s], S.O1[dt]); S.O2[dt] = MFMA16(vt[d2][s], p2[s], S.O2[dt]); }
;         __builtin_amdgcn_s_setprio(0);
;         __builtin_amdgcn_sched_barrier(0);
;     }
; }
; template <int VAR>
; DI void attn_tile(AtState& S, const LAS unsigned char* buf, const bf16x8 q1, const bf16x8 q2, int kt, bool diag, int qpos0, int qpos_l, float slope2, float adv, float decay, int hh, int fr, int fq) {
;     ...
;         const float nref = fmaxf(S.ref, mx);
;         const float alpha = fast_exp2(S.ref - nref); S.ref = nref;
; #pragma unroll
;         for (int k4 = 0; k4 < 4; ++k4) { s1[k4] = s1[k4] - nref; s2[k4] = s2[k4] - nref; }
;         if (kt == 0) { const float c0 = -slope2 * (float)qpos0 - S.ref;
; #pragma unroll
;             for (int k4 = 0; k4 < 4; ++k4)
; #pragma unroll
;                 for (int j = 0; j < 4; ++j) S.cinit[k4][j] = slope2 * (float)(16 * k4 + j - ql) + c0; }
;         at_exp(s1, s2, ps1, ps2);
;         at_pv(S, s1, s2, alpha, ps1, ps2, buf, hh, fq, tq, tp);
.LBB0_1413:
	v_sub_f32_e32 v63, v94, v117
	v_sub_f32_e32 v69, v92, v117
	v_sub_f32_e32 v70, v90, v117
	v_sub_f32_e32 v3, v3, v117
	v_sub_f32_e32 v71, v93, v117
	v_sub_f32_e32 v72, v91, v117
	v_sub_f32_e32 v73, v89, v117
	v_sub_f32_e32 v78, v88, v117
	v_sub_f32_e32 v79, v102, v117
	v_sub_f32_e32 v80, v100, v117
	v_sub_f32_e32 v81, v98, v117
	v_sub_f32_e32 v83, v96, v117
	v_sub_f32_e32 v90, v101, v117
	v_sub_f32_e32 v91, v99, v117
	v_sub_f32_e32 v92, v97, v117
	v_sub_f32_e32 v93, v95, v117
	v_sub_f32_e32 v99, v109, v117
	v_sub_f32_e32 v100, v108, v117
	v_exp_f32_e32 v84, v3
	v_exp_f32_e32 v86, v78
	v_exp_f32_e32 v85, v70
	v_exp_f32_e32 v87, v73
	v_exp_f32_e32 v88, v69
	v_exp_f32_e32 v89, v63
	v_exp_f32_e32 v108, v72
	v_exp_f32_e32 v109, v71
	v_sub_f32_e32 v94, v106, v117
	v_sub_f32_e32 v95, v105, v117
	v_sub_f32_e32 v96, v104, v117
	v_sub_f32_e32 v97, v103, v117
	v_sub_f32_e32 v77, v77, v117
	v_sub_f32_e32 v76, v76, v117
	v_sub_f32_e32 v75, v75, v117
	v_sub_f32_e32 v74, v74, v117
	v_sub_f32_e32 v101, v107, v117
	v_exp_f32_e32 v104, v83
	v_exp_f32_e32 v162, v93
	v_exp_f32_e32 v105, v81
	v_exp_f32_e32 v106, v80
	v_exp_f32_e32 v107, v79
	v_exp_f32_e32 v164, v91
	v_exp_f32_e32 v165, v90
	v_exp_f32_e32 v163, v92
	v_sub_f32_e32 v98, v68, v117
	v_sub_f32_e32 v102, v65, v117
	v_sub_f32_e32 v103, v64, v117
	v_sub_f32_e32 v158, v67, v117
	v_sub_f32_e32 v159, v66, v117
	v_exp_f32_e32 v166, v97
	v_exp_f32_e32 v168, v74
	v_exp_f32_e32 v167, v96
	v_exp_f32_e32 v169, v75
	v_exp_f32_e32 v170, v95
	v_exp_f32_e32 v171, v94
	v_exp_f32_e32 v172, v76
	v_exp_f32_e32 v173, v77
	v_sub_f32_e32 v62, v212, v117
	v_exp_f32_e32 v174, v101
	v_exp_f32_e32 v176, v159
	v_exp_f32_e32 v175, v100
	v_exp_f32_e32 v178, v99
	v_exp_f32_e32 v179, v98
	v_exp_f32_e32 v180, v103
	v_exp_f32_e32 v181, v102
	v_exp_f32_e32 v177, v158
	v_exp_f32_e32 v82, v62
	v_pk_add_f32 v[64:65], v[106:107], v[88:89]
	v_pk_add_f32 v[62:63], v[104:105], v[84:85]
	v_pk_add_f32 v[68:69], v[164:165], v[108:109]
	v_pk_add_f32 v[66:67], v[162:163], v[86:87]
	v_pk_add_f32 v[62:63], v[166:167], v[62:63]
	v_pk_add_f32 v[64:65], v[170:171], v[64:65]
	v_pk_add_f32 v[66:67], v[168:169], v[66:67]
	v_pk_add_f32 v[68:69], v[172:173], v[68:69]
	v_pk_add_f32 v[64:65], v[178:179], v[64:65]
	v_pk_add_f32 v[62:63], v[174:175], v[62:63]
	v_pk_add_f32 v[68:69], v[180:181], v[68:69]
	v_pk_add_f32 v[66:67], v[176:177], v[66:67]
	v_mov_b32_e32 v71, v62
	v_mov_b32_e32 v70, v66
	v_mov_b32_e32 v62, v67
	v_mov_b32_e32 v66, v68
	v_mov_b32_e32 v67, v64
	v_mov_b32_e32 v64, v69
	v_pk_add_f32 v[62:63], v[70:71], v[62:63]
	v_pk_add_f32 v[64:65], v[66:67], v[64:65]
	v_add3_u32 v3, s28, v208, v209
	v_pk_add_f32 v[62:63], v[62:63], v[64:65]
	v_pk_mul_f32 v[64:65], v[154:155], v[82:83] op_sel_hi:[1,0]
	v_pk_fma_f32 v[158:159], v[156:157], v[82:83], v[62:63] op_sel_hi:[1,0,1]
	v_pk_mul_f32 v[62:63], v[152:153], v[82:83] op_sel_hi:[1,0]
	v_pk_mul_f32 v[68:69], v[150:151], v[82:83] op_sel_hi:[1,0]
	v_pk_mul_f32 v[66:67], v[148:149], v[82:83] op_sel_hi:[1,0]
	v_pk_mul_f32 v[72:73], v[146:147], v[82:83] op_sel_hi:[1,0]
	v_pk_mul_f32 v[70:71], v[144:145], v[82:83] op_sel_hi:[1,0]
	v_pk_mul_f32 v[76:77], v[138:139], v[82:83] op_sel_hi:[1,0]
	v_pk_mul_f32 v[74:75], v[136:137], v[82:83] op_sel_hi:[1,0]
	v_pk_mul_f32 v[80:81], v[134:135], v[82:83] op_sel_hi:[1,0]
	v_pk_mul_f32 v[78:79], v[132:133], v[82:83] op_sel_hi:[1,0]
	v_pk_mul_f32 v[92:93], v[130:131], v[82:83] op_sel_hi:[1,0]
	v_pk_mul_f32 v[90:91], v[128:129], v[82:83] op_sel_hi:[1,0]
	v_pk_mul_f32 v[96:97], v[126:127], v[82:83] op_sel_hi:[1,0]
	v_pk_mul_f32 v[94:95], v[124:125], v[82:83] op_sel_hi:[1,0]
	v_pk_mul_f32 v[100:101], v[4:5], v[82:83] op_sel_hi:[1,0]
	v_pk_mul_f32 v[98:99], v[122:123], v[82:83] op_sel_hi:[1,0]
	v_cvt_pk_bf16_f32 v102, v84, v85
	v_cvt_pk_bf16_f32 v103, v88, v89
	v_cvt_pk_bf16_f32 v104, v104, v105
	v_cvt_pk_bf16_f32 v105, v106, v107
	v_cvt_pk_bf16_f32 v106, v86, v87
	ds_read_b64_tr_b16 v[82:83], v3 offset:17408
	ds_read_b64_tr_b16 v[86:87], v3 offset:17440
	ds_read_b64_tr_b16 v[84:85], v3 offset:22016
	ds_read_b64_tr_b16 v[88:89], v3 offset:22048
	ds_read_b64_tr_b16 v[126:127], v3 offset:26624
	ds_read_b64_tr_b16 v[128:129], v3 offset:31232
	ds_read_b64_tr_b16 v[132:133], v3 offset:31264
	ds_read_b64_tr_b16 v[130:131], v3 offset:26656
	v_cvt_pk_bf16_f32 v107, v108, v109
	v_cvt_pk_bf16_f32 v108, v162, v163
	v_cvt_pk_bf16_f32 v109, v164, v165
	v_cvt_pk_bf16_f32 v122, v166, v167
	v_cvt_pk_bf16_f32 v123, v170, v171
	v_cvt_pk_bf16_f32 v124, v174, v175
	v_cvt_pk_bf16_f32 v125, v178, v179
	v_cvt_pk_bf16_f32 v134, v168, v169
	v_cvt_pk_bf16_f32 v135, v172, v173
	v_cvt_pk_bf16_f32 v136, v176, v177
	v_cvt_pk_bf16_f32 v137, v180, v181
	s_waitcnt lgkmcnt(5)
	v_mfma_f32_16x16x32_bf16 v[62:65], v[82:85], v[102:105], v[62:65]
	v_mfma_f32_16x16x32_bf16 v[82:85], v[82:85], v[106:109], v[66:69]
	s_waitcnt lgkmcnt(4)
	v_mfma_f32_16x16x32_bf16 v[70:73], v[86:89], v[102:105], v[70:73]
	v_mfma_f32_16x16x32_bf16 v[74:77], v[86:89], v[106:109], v[74:77]
	s_waitcnt lgkmcnt(2)
	v_mfma_f32_16x16x32_bf16 v[66:69], v[126:129], v[122:125], v[62:65]
	v_mfma_f32_16x16x32_bf16 v[86:89], v[126:129], v[134:137], v[82:85]
	s_waitcnt lgkmcnt(0)
	v_mfma_f32_16x16x32_bf16 v[70:73], v[130:133], v[122:125], v[70:73]
	v_mfma_f32_16x16x32_bf16 v[82:85], v[130:133], v[134:137], v[74:77]
	ds_read_b64_tr_b16 v[62:63], v3 offset:17472
	s_nop 0
	ds_read_b64_tr_b16 v[74:75], v3 offset:17504
	ds_read_b64_tr_b16 v[64:65], v3 offset:22080
	ds_read_b64_tr_b16 v[76:77], v3 offset:22112
	ds_read_b64_tr_b16 v[126:127], v3 offset:26688
	ds_read_b64_tr_b16 v[128:129], v3 offset:31296
	ds_read_b64_tr_b16 v[132:133], v3 offset:31328
	ds_read_b64_tr_b16 v[130:131], v3 offset:26720
	s_waitcnt lgkmcnt(5)
	v_mfma_f32_16x16x32_bf16 v[78:81], v[62:65], v[102:105], v[78:81]
	v_mfma_f32_16x16x32_bf16 v[62:65], v[62:65], v[106:109], v[90:93]
	s_waitcnt lgkmcnt(4)
	v_mfma_f32_16x16x32_bf16 v[90:93], v[74:77], v[102:105], v[94:97]
	v_mfma_f32_16x16x32_bf16 v[74:77], v[74:77], v[106:109], v[98:101]
	s_waitcnt lgkmcnt(2)
	v_mfma_f32_16x16x32_bf16 v[94:97], v[126:129], v[122:125], v[78:81]
	v_mfma_f32_16x16x32_bf16 v[106:109], v[126:129], v[134:137], v[62:65]
	s_waitcnt lgkmcnt(0)
	v_mfma_f32_16x16x32_bf16 v[98:101], v[130:133], v[122:125], v[90:93]
	v_mfma_f32_16x16x32_bf16 v[102:105], v[130:133], v[134:137], v[74:77]
	v_mov_b64_e32 v[64:65], v[48:49]
	s_nop 0
	v_mov_b64_e32 v[76:77], v[52:53]
	v_mov_b64_e32 v[80:81], v[56:57]
	v_mov_b64_e32 v[92:93], v[60:61]
	v_mov_b64_e32 v[62:63], v[46:47]
	v_mov_b64_e32 v[74:75], v[50:51]
	v_mov_b64_e32 v[78:79], v[54:55]
	v_mov_b64_e32 v[90:91], v[58:59]

; #define DEAL_LOOP(F, ctr, N, BODY) do { gu32* _c = (ctr); int u = F.bid; while (u < (N)) { const unsigned _t = deal_prefetch(F, _c); BODY; u = deal_publish(F, _t) + F.G; } __syncthreads(); } while (0)
; #define REPBAR(k) do { if (rep + 1 < REPS(k)) xcd_barrier(bar); } while (0)
; DI void wait_done(const Frame& F, gu32* ctr, unsigned need) {
;     if (F.tid == 0) { unsigned sp = 0; while (__hip_atomic_load(ctr, RLX_AGENT) < need) { __builtin_amdgcn_s_sleep(2); if (++sp > (1u << 22)) break; }
;         __builtin_amdgcn_fence(__ATOMIC_ACQUIRE, "agent"); asm volatile("s_waitcnt vmcnt(0)" ::: "memory"); }
;     __syncthreads();
; __global__ void __launch_bounds__(NTHR, 2) fwd(Args args) {
;     ...
;                 if (PH_ON(8)) DEAL_LOOP(F, cnt_word(F, l, CNT_ATTN + 5 * rep), AT_UNITS, attn_unit<0>(args, F, l, u));
;                 REPBAR(8); }
;             wait_done(F, cnt_word(F, l, CNT_SSM1DONE), (unsigned)F.G);
.LBB0_1420:
	s_setprio 0
	s_lshl_b64 s[0:1], s[4:5], 2
	v_readlane_b32 s2, v252, 3
	s_add_u32 s6, s2, s0
	v_readlane_b32 s0, v252, 4
	s_addc_u32 s7, s0, s1
	v_cmp_eq_u32_e32 vcc, 0, v0
	s_waitcnt vmcnt(0)
	s_barrier
	s_and_saveexec_b64 s[0:1], vcc
	s_xor_b64 s[0:1], exec, s[0:1]
	s_cbranch_execz .LBB0_1430
	s_mov_b32 s4, 0x400001
	s_branch .LBB0_1423
